# hand-written PV loop, merge rescale, SGU MFMA loop; sample-conv staging waits trimmed
# speedup vs baseline: 1.0262x; 1.0144x over previous
.LBB0_46:
	s_lshl_b32 s1, s16, 5
	s_and_b32 s0, s16, 0x100
	s_and_b32 s1, s1, 0xe0
	s_or_b32 s0, s1, s0
	s_bfe_u32 s1, s16, 0x50003
	s_or_b32 s4, s0, s1
	s_and_b64 s[0:1], s[84:85], exec
	s_cselect_b32 s17, s4, s16
	s_waitcnt lgkmcnt(0)
	v_mov_b32_e32 v129, v214
	s_ashr_i32 s23, s17, 6
	s_bfe_u32 s25, s17, 0x20004
	s_lshl_b32 s17, s17, 7
	s_add_i32 s4, s23, s19
	s_lshl_b32 s23, s23, 11
	s_and_b32 s17, s17, 0x780
	v_ashrrev_i32_e32 v0, 2, v129
	v_bfi_b32 v0, -16, v0, v129
	s_or_b32 s17, s23, s17
	s_ashr_i32 s5, s4, 31
	v_add_u32_e32 v0, s17, v0
	s_mov_b64 s[26:27], s[42:43]
	v_ashrrev_i32_e32 v1, 31, v0
	s_lshl_b64 s[4:5], s[4:5], 19
	s_lshl_b32 s17, s25, 17
	s_mov_b64 s[0:1], s[42:43]
	s_mov_b64 s[28:29], s[42:43]
	v_lshlrev_b64 v[140:141], 11, v[0:1]
	s_lshl_b32 s82, s25, 9
	s_or_b32 s4, s4, s17
	v_bfe_u32 v174, v129, 4, 2
	s_add_u32 s26, s26, s4
	v_lshl_add_u64 v[0:1], s[28:29], 0, v[140:141]
	v_lshlrev_b32_e32 v34, 3, v129
	v_lshlrev_b32_e32 v32, 4, v129
	v_lshl_add_u64 v[0:1], v[0:1], 0, s[82:83]
	v_lshlrev_b32_e32 v102, 4, v174
	v_mov_b32_e32 v103, v193
	s_addc_u32 s27, s27, s5
	v_and_b32_e32 v80, 0x1f0, v32
	v_mov_b32_e32 v81, v193
	v_and_b32_e32 v122, 0xffffff00, v34
	v_lshl_add_u64 v[0:1], v[0:1], 0, v[102:103]
	s_mov_b64 s[28:29], 0xfc00000
	v_lshl_add_u64 v[32:33], s[26:27], 0, v[80:81]
	s_mov_b64 s[26:27], 0x6400000
	v_ashrrev_i32_e32 v123, 31, v122
	v_lshl_add_u64 v[2:3], v[0:1], 0, s[28:29]
	v_add_co_u32_e32 v0, vcc, s31, v0
	v_lshl_add_u64 v[120:121], v[32:33], 0, s[26:27]
	v_lshlrev_b64 v[82:83], 1, v[122:123]
	v_addc_co_u32_e32 v1, vcc, 0, v1, vcc
	v_lshl_add_u64 v[32:33], v[120:121], 0, v[82:83]
	global_load_dwordx4 v[24:27], v[2:3], off offset:64
	global_load_dwordx4 v[20:23], v[2:3], off offset:128
	global_load_dwordx4 v[16:19], v[2:3], off offset:192
	global_load_dwordx4 v[12:15], v[2:3], off offset:256
	global_load_dwordx4 v[8:11], v[2:3], off offset:320
	global_load_dwordx4 v[4:7], v[2:3], off offset:384
	global_load_dwordx4 v[28:31], v[0:1], off
	s_nop 0
	global_load_dwordx4 v[0:3], v[2:3], off offset:448
	v_add_u32_e32 v36, 0x1000, v122
	global_load_dwordx4 v[32:35], v[32:33], off
	v_add_u32_e32 v40, 0x2000, v122
	v_add_u32_e32 v44, 0x3000, v122
	v_add_u32_e32 v48, 0x4000, v122
	v_add_u32_e32 v52, 0x5000, v122
	v_add_u32_e32 v56, 0x6000, v122
	v_add_u32_e32 v60, 0x7000, v122
	v_add_u32_e32 v64, 0x8000, v122
	v_add_u32_e32 v68, 0x9000, v122
	v_add_u32_e32 v72, 0xa000, v122
	v_add_u32_e32 v76, 0xb000, v122
	v_add_u32_e32 v98, 0xc000, v122
	v_ashrrev_i32_e32 v37, 31, v36
	v_ashrrev_i32_e32 v41, 31, v40
	v_ashrrev_i32_e32 v45, 31, v44
	v_ashrrev_i32_e32 v49, 31, v48
	v_ashrrev_i32_e32 v53, 31, v52
	v_ashrrev_i32_e32 v57, 31, v56
	v_ashrrev_i32_e32 v61, 31, v60
	v_ashrrev_i32_e32 v65, 31, v64
	v_ashrrev_i32_e32 v69, 31, v68
	v_ashrrev_i32_e32 v73, 31, v72
	v_ashrrev_i32_e32 v77, 31, v76
	v_ashrrev_i32_e32 v99, 31, v98
	v_add_u32_e32 v108, 0xd000, v122
	v_add_u32_e32 v116, 0xe000, v122
	v_add_u32_e32 v122, 0xf000, v122
	v_lshlrev_b64 v[84:85], 1, v[36:37]
	v_lshlrev_b64 v[86:87], 1, v[40:41]
	v_lshlrev_b64 v[88:89], 1, v[44:45]
	v_lshlrev_b64 v[90:91], 1, v[48:49]
	v_lshlrev_b64 v[92:93], 1, v[52:53]
	v_lshlrev_b64 v[94:95], 1, v[56:57]
	v_lshlrev_b64 v[96:97], 1, v[60:61]
	v_lshlrev_b64 v[104:105], 1, v[64:65]
	v_lshlrev_b64 v[106:107], 1, v[68:69]
	v_lshlrev_b64 v[112:113], 1, v[72:73]
	v_lshlrev_b64 v[114:115], 1, v[76:77]
	v_lshlrev_b64 v[124:125], 1, v[98:99]
	v_ashrrev_i32_e32 v109, 31, v108
	v_ashrrev_i32_e32 v117, 31, v116
	v_ashrrev_i32_e32 v123, 31, v122
	v_lshl_add_u64 v[36:37], v[120:121], 0, v[84:85]
	v_lshl_add_u64 v[40:41], v[120:121], 0, v[86:87]
	v_lshl_add_u64 v[44:45], v[120:121], 0, v[88:89]
	v_lshl_add_u64 v[48:49], v[120:121], 0, v[90:91]
	v_lshl_add_u64 v[52:53], v[120:121], 0, v[92:93]
	v_lshl_add_u64 v[56:57], v[120:121], 0, v[94:95]
	v_lshl_add_u64 v[60:61], v[120:121], 0, v[96:97]
	v_lshl_add_u64 v[64:65], v[120:121], 0, v[104:105]
	v_lshl_add_u64 v[68:69], v[120:121], 0, v[106:107]
	v_lshl_add_u64 v[72:73], v[120:121], 0, v[112:113]
	v_lshl_add_u64 v[76:77], v[120:121], 0, v[114:115]
	v_lshl_add_u64 v[98:99], v[120:121], 0, v[124:125]
	v_lshlrev_b64 v[126:127], 1, v[108:109]
	v_lshlrev_b64 v[132:133], 1, v[116:117]
	v_lshlrev_b64 v[134:135], 1, v[122:123]
	global_load_dwordx4 v[36:39], v[36:37], off
	v_lshl_add_u64 v[108:109], v[120:121], 0, v[126:127]
	global_load_dwordx4 v[40:43], v[40:41], off
	v_lshl_add_u64 v[116:117], v[120:121], 0, v[132:133]
	global_load_dwordx4 v[44:47], v[44:45], off
	v_lshl_add_u64 v[120:121], v[120:121], 0, v[134:135]
	global_load_dwordx4 v[48:51], v[48:49], off
	v_add_u32_e32 v128, 0, v80
	global_load_dwordx4 v[52:55], v[52:53], off
	v_ashrrev_i32_e32 v103, 5, v129
	global_load_dwordx4 v[56:59], v[56:57], off
	v_mad_u64_u32 v[142:143], s[26:27], v103, s34, v[128:129]
	global_load_dwordx4 v[60:63], v[60:61], off
	v_and_b32_e32 v130, 15, v129
	global_load_dwordx4 v[64:67], v[64:65], off
	v_mul_u32_u24_e32 v143, 0x210, v130
	global_load_dwordx4 v[68:71], v[68:69], off
	s_add_u32 s0, s0, s4
	global_load_dwordx4 v[72:75], v[72:73], off
	s_addc_u32 s1, s1, s5
	global_load_dwordx4 v[76:79], v[76:77], off
	v_cmp_lt_i32_e32 vcc, v223, v218
	global_load_dwordx4 v[98:101], v[98:99], off
	v_lshlrev_b32_e32 v192, 3, v174
	global_load_dwordx4 v[108:111], v[108:109], off
	s_nop 0
	global_load_dwordx4 v[116:119], v[116:117], off
	s_nop 0
	global_load_dwordx4 v[120:123], v[120:121], off
	s_waitcnt vmcnt(0) lgkmcnt(0)
	ds_write_b128 v142, v[32:35]
	v_add_u32_e32 v32, 0x200, v129
	v_ashrrev_i32_e32 v32, 5, v32
	v_mad_u64_u32 v[144:145], s[26:27], v32, s34, v[128:129]
	v_add_u32_e32 v32, 0x400, v129
	v_ashrrev_i32_e32 v32, 5, v32
	v_mad_u64_u32 v[146:147], s[26:27], v32, s34, v[128:129]
	v_add_u32_e32 v32, 0x600, v129
	v_ashrrev_i32_e32 v32, 5, v32
	v_mad_u64_u32 v[148:149], s[26:27], v32, s34, v[128:129]
	v_add_u32_e32 v32, 0x800, v129
	v_ashrrev_i32_e32 v32, 5, v32
	v_mad_u64_u32 v[150:151], s[26:27], v32, s34, v[128:129]
	v_add_u32_e32 v32, 0xa00, v129
	v_ashrrev_i32_e32 v32, 5, v32
	v_mad_u64_u32 v[152:153], s[26:27], v32, s34, v[128:129]
	v_add_u32_e32 v32, 0xc00, v129
	v_ashrrev_i32_e32 v32, 5, v32
	v_mad_u64_u32 v[154:155], s[26:27], v32, s34, v[128:129]
	v_add_u32_e32 v32, 0xe00, v129
	v_ashrrev_i32_e32 v32, 5, v32
	v_mad_u64_u32 v[156:157], s[26:27], v32, s34, v[128:129]
	v_add_u32_e32 v32, 0x1000, v129
	v_ashrrev_i32_e32 v32, 5, v32
	v_mad_u64_u32 v[158:159], s[26:27], v32, s34, v[128:129]
	v_add_u32_e32 v32, 0x1200, v129
	v_ashrrev_i32_e32 v32, 5, v32
	v_mad_u64_u32 v[160:161], s[26:27], v32, s34, v[128:129]
	v_add_u32_e32 v32, 0x1400, v129
	v_ashrrev_i32_e32 v32, 5, v32
	v_mad_u64_u32 v[162:163], s[26:27], v32, s34, v[128:129]
	v_add_u32_e32 v32, 0x1600, v129
	v_ashrrev_i32_e32 v32, 5, v32
	v_mad_u64_u32 v[164:165], s[26:27], v32, s34, v[128:129]
	v_add_u32_e32 v32, 0x1800, v129
	v_ashrrev_i32_e32 v32, 5, v32
	v_mad_u64_u32 v[166:167], s[26:27], v32, s34, v[128:129]
	v_add_u32_e32 v32, 0x1a00, v129
	v_ashrrev_i32_e32 v32, 5, v32
	v_mad_u64_u32 v[168:169], s[26:27], v32, s34, v[128:129]
	v_add_u32_e32 v32, 0x1c00, v129
	v_ashrrev_i32_e32 v32, 5, v32
	v_mad_u64_u32 v[170:171], s[26:27], v32, s34, v[128:129]
	v_add_u32_e32 v32, 0x1e00, v129
	v_ashrrev_i32_e32 v32, 5, v32
	ds_write_b128 v144, v[36:39]
	ds_write_b128 v146, v[40:43]
	ds_write_b128 v148, v[44:47]
	ds_write_b128 v150, v[48:51]
	ds_write_b128 v152, v[52:55]
	ds_write_b128 v154, v[56:59]
	ds_write_b128 v156, v[60:63]
	ds_write_b128 v158, v[64:67]
	ds_write_b128 v160, v[68:71]
	v_mad_u64_u32 v[172:173], s[26:27], v32, s34, v[128:129]
	ds_write_b128 v162, v[72:75]
	ds_write_b128 v164, v[76:79]
	ds_write_b128 v166, v[98:101]
	v_add3_u32 v98, 0, v143, v102
	ds_write_b128 v168, v[108:111]
	v_add_u32_e32 v99, 0x10800, v98
	ds_write_b128 v170, v[116:119]
	v_add_u32_e32 v108, 0x12900, v98
	ds_write_b128 v172, v[120:123]
	s_waitcnt lgkmcnt(0)
	s_barrier
	ds_read_b128 v[32:35], v98
	ds_read_b128 v[36:39], v98 offset:64
	ds_read_b128 v[40:43], v98 offset:8448
	ds_read_b128 v[44:47], v98 offset:8512
	s_waitcnt lgkmcnt(3)
	v_mfma_f32_16x16x32_bf16 v[32:35], v[32:35], v[28:31], 0
	v_add_u32_e32 v120, 0x16b00, v98
	v_add_u32_e32 v136, 0x1ad00, v98
	s_waitcnt lgkmcnt(1)
	v_mfma_f32_16x16x32_bf16 v[40:43], v[40:43], v[28:31], 0
	v_mfma_f32_16x16x32_bf16 v[32:35], v[36:39], v[24:27], v[32:35]
	s_waitcnt lgkmcnt(0)
	v_mfma_f32_16x16x32_bf16 v[36:39], v[44:47], v[24:27], v[40:43]
	s_nop 4
	ds_read_b128 v[40:43], v98 offset:128
	ds_read_b128 v[44:47], v98 offset:192
	s_waitcnt lgkmcnt(1)
	v_mfma_f32_16x16x32_bf16 v[32:35], v[40:43], v[20:23], v[32:35]
	ds_read_b128 v[40:43], v98 offset:8576
	ds_read_b128 v[48:51], v98 offset:8640
	s_waitcnt lgkmcnt(1)
	v_mfma_f32_16x16x32_bf16 v[36:39], v[40:43], v[20:23], v[36:39]
	v_mfma_f32_16x16x32_bf16 v[32:35], v[44:47], v[16:19], v[32:35]
	ds_read_b128 v[40:43], v98 offset:256
	ds_read_b128 v[44:47], v98 offset:320
	s_waitcnt lgkmcnt(2)
	v_mfma_f32_16x16x32_bf16 v[36:39], v[48:51], v[16:19], v[36:39]
	s_waitcnt lgkmcnt(1)
	v_mfma_f32_16x16x32_bf16 v[32:35], v[40:43], v[12:15], v[32:35]
	ds_read_b128 v[40:43], v98 offset:8704
	ds_read_b128 v[48:51], v98 offset:8768
	s_waitcnt lgkmcnt(1)
	v_mfma_f32_16x16x32_bf16 v[36:39], v[40:43], v[12:15], v[36:39]
	v_mfma_f32_16x16x32_bf16 v[32:35], v[44:47], v[8:11], v[32:35]
	ds_read_b128 v[40:43], v98 offset:384
	ds_read_b128 v[44:47], v98 offset:448
	s_waitcnt lgkmcnt(2)
	v_mfma_f32_16x16x32_bf16 v[36:39], v[48:51], v[8:11], v[36:39]
	s_waitcnt lgkmcnt(1)
	v_mfma_f32_16x16x32_bf16 v[32:35], v[40:43], v[4:7], v[32:35]
	ds_read_b128 v[40:43], v98 offset:8832
	ds_read_b128 v[48:51], v98 offset:8896
	s_waitcnt lgkmcnt(1)
	v_mfma_f32_16x16x32_bf16 v[40:43], v[40:43], v[4:7], v[36:39]
	v_mfma_f32_16x16x32_bf16 v[36:39], v[44:47], v[0:3], v[32:35]
	s_waitcnt lgkmcnt(0)
	v_mfma_f32_16x16x32_bf16 v[32:35], v[48:51], v[0:3], v[40:43]
	s_nop 4
	ds_read_b128 v[40:43], v98 offset:16896
	ds_read_b128 v[44:47], v98 offset:16960
	ds_read_b128 v[48:51], v98 offset:25344
	ds_read_b128 v[52:55], v98 offset:25408
	s_waitcnt lgkmcnt(3)
	v_mfma_f32_16x16x32_bf16 v[40:43], v[40:43], v[28:31], 0
	s_waitcnt lgkmcnt(1)
	v_mfma_f32_16x16x32_bf16 v[48:51], v[48:51], v[28:31], 0
	v_mfma_f32_16x16x32_bf16 v[40:43], v[44:47], v[24:27], v[40:43]
	s_waitcnt lgkmcnt(0)
	v_mfma_f32_16x16x32_bf16 v[44:47], v[52:55], v[24:27], v[48:51]
	s_nop 4
	ds_read_b128 v[48:51], v98 offset:17024
	ds_read_b128 v[52:55], v98 offset:17088
	s_waitcnt lgkmcnt(1)
	v_mfma_f32_16x16x32_bf16 v[40:43], v[48:51], v[20:23], v[40:43]
	ds_read_b128 v[48:51], v98 offset:25472
	ds_read_b128 v[56:59], v98 offset:25536
	s_waitcnt lgkmcnt(1)
	v_mfma_f32_16x16x32_bf16 v[44:47], v[48:51], v[20:23], v[44:47]
	v_mfma_f32_16x16x32_bf16 v[40:43], v[52:55], v[16:19], v[40:43]
	ds_read_b128 v[48:51], v98 offset:17152
	ds_read_b128 v[52:55], v98 offset:17216
	s_waitcnt lgkmcnt(2)
	v_mfma_f32_16x16x32_bf16 v[44:47], v[56:59], v[16:19], v[44:47]
	s_waitcnt lgkmcnt(1)
	v_mfma_f32_16x16x32_bf16 v[40:43], v[48:51], v[12:15], v[40:43]
	ds_read_b128 v[48:51], v98 offset:25600
	ds_read_b128 v[56:59], v98 offset:25664
	s_waitcnt lgkmcnt(1)
	v_mfma_f32_16x16x32_bf16 v[44:47], v[48:51], v[12:15], v[44:47]
	v_mfma_f32_16x16x32_bf16 v[40:43], v[52:55], v[8:11], v[40:43]
	ds_read_b128 v[48:51], v98 offset:17280
	ds_read_b128 v[52:55], v98 offset:17344
	s_waitcnt lgkmcnt(2)
	v_mfma_f32_16x16x32_bf16 v[44:47], v[56:59], v[8:11], v[44:47]
	s_waitcnt lgkmcnt(1)
	v_mfma_f32_16x16x32_bf16 v[40:43], v[48:51], v[4:7], v[40:43]
	ds_read_b128 v[48:51], v98 offset:25728
	ds_read_b128 v[56:59], v98 offset:25792
	s_waitcnt lgkmcnt(1)
	v_mfma_f32_16x16x32_bf16 v[48:51], v[48:51], v[4:7], v[44:47]
	v_mfma_f32_16x16x32_bf16 v[44:47], v[52:55], v[0:3], v[40:43]
	s_waitcnt lgkmcnt(0)
	v_mfma_f32_16x16x32_bf16 v[40:43], v[56:59], v[0:3], v[48:51]
	s_nop 4
	ds_read_b128 v[48:51], v98 offset:33792
	ds_read_b128 v[52:55], v98 offset:33856
	ds_read_b128 v[56:59], v98 offset:42240
	ds_read_b128 v[60:63], v98 offset:42304
	s_waitcnt lgkmcnt(3)
	v_mfma_f32_16x16x32_bf16 v[48:51], v[48:51], v[28:31], 0
	s_waitcnt lgkmcnt(1)
	v_mfma_f32_16x16x32_bf16 v[56:59], v[56:59], v[28:31], 0
	v_mfma_f32_16x16x32_bf16 v[48:51], v[52:55], v[24:27], v[48:51]
	s_waitcnt lgkmcnt(0)
	v_mfma_f32_16x16x32_bf16 v[52:55], v[60:63], v[24:27], v[56:59]
	s_nop 4
	ds_read_b128 v[56:59], v98 offset:33920
	ds_read_b128 v[60:63], v98 offset:33984
	s_waitcnt lgkmcnt(1)
	v_mfma_f32_16x16x32_bf16 v[48:51], v[56:59], v[20:23], v[48:51]
	ds_read_b128 v[56:59], v98 offset:42368
	ds_read_b128 v[64:67], v98 offset:42432
	s_waitcnt lgkmcnt(1)
	v_mfma_f32_16x16x32_bf16 v[52:55], v[56:59], v[20:23], v[52:55]
	v_mfma_f32_16x16x32_bf16 v[48:51], v[60:63], v[16:19], v[48:51]
	ds_read_b128 v[56:59], v98 offset:34048
	ds_read_b128 v[60:63], v98 offset:34112
	s_waitcnt lgkmcnt(2)
	v_mfma_f32_16x16x32_bf16 v[52:55], v[64:67], v[16:19], v[52:55]
	s_waitcnt lgkmcnt(1)
	v_mfma_f32_16x16x32_bf16 v[48:51], v[56:59], v[12:15], v[48:51]
	ds_read_b128 v[56:59], v98 offset:42496
	ds_read_b128 v[64:67], v98 offset:42560
	s_waitcnt lgkmcnt(1)
	v_mfma_f32_16x16x32_bf16 v[52:55], v[56:59], v[12:15], v[52:55]
	v_mfma_f32_16x16x32_bf16 v[48:51], v[60:63], v[8:11], v[48:51]
	ds_read_b128 v[56:59], v98 offset:34176
	ds_read_b128 v[60:63], v98 offset:34240
	s_waitcnt lgkmcnt(2)
	v_mfma_f32_16x16x32_bf16 v[52:55], v[64:67], v[8:11], v[52:55]
	s_waitcnt lgkmcnt(1)
	v_mfma_f32_16x16x32_bf16 v[48:51], v[56:59], v[4:7], v[48:51]
	ds_read_b128 v[56:59], v98 offset:42624
	ds_read_b128 v[64:67], v98 offset:42688
	s_waitcnt lgkmcnt(1)
	v_mfma_f32_16x16x32_bf16 v[56:59], v[56:59], v[4:7], v[52:55]
	v_mfma_f32_16x16x32_bf16 v[52:55], v[60:63], v[0:3], v[48:51]
	s_waitcnt lgkmcnt(0)
	v_mfma_f32_16x16x32_bf16 v[48:51], v[64:67], v[0:3], v[56:59]
	s_nop 4
	ds_read_b128 v[56:59], v98 offset:50688
	ds_read_b128 v[60:63], v98 offset:50752
	ds_read_b128 v[64:67], v98 offset:59136
	ds_read_b128 v[68:71], v98 offset:59200
	s_waitcnt lgkmcnt(3)
	v_mfma_f32_16x16x32_bf16 v[56:59], v[56:59], v[28:31], 0
	s_waitcnt lgkmcnt(1)
	v_mfma_f32_16x16x32_bf16 v[64:67], v[64:67], v[28:31], 0
	v_mfma_f32_16x16x32_bf16 v[56:59], v[60:63], v[24:27], v[56:59]
	s_waitcnt lgkmcnt(0)
	v_mfma_f32_16x16x32_bf16 v[60:63], v[68:71], v[24:27], v[64:67]
	s_nop 4
	ds_read_b128 v[64:67], v98 offset:50816
	ds_read_b128 v[68:71], v98 offset:50880
	s_waitcnt lgkmcnt(1)
	v_mfma_f32_16x16x32_bf16 v[56:59], v[64:67], v[20:23], v[56:59]
	ds_read_b128 v[64:67], v98 offset:59264
	ds_read_b128 v[72:75], v98 offset:59328
	s_waitcnt lgkmcnt(1)
	v_mfma_f32_16x16x32_bf16 v[60:63], v[64:67], v[20:23], v[60:63]
	v_mfma_f32_16x16x32_bf16 v[56:59], v[68:71], v[16:19], v[56:59]
	ds_read_b128 v[64:67], v98 offset:50944
	ds_read_b128 v[68:71], v98 offset:51008
	s_waitcnt lgkmcnt(2)
	v_mfma_f32_16x16x32_bf16 v[60:63], v[72:75], v[16:19], v[60:63]
	s_waitcnt lgkmcnt(1)
	v_mfma_f32_16x16x32_bf16 v[56:59], v[64:67], v[12:15], v[56:59]
	ds_read_b128 v[64:67], v98 offset:59392
	ds_read_b128 v[72:75], v98 offset:59456
	s_waitcnt lgkmcnt(1)
	v_mfma_f32_16x16x32_bf16 v[60:63], v[64:67], v[12:15], v[60:63]
	v_mfma_f32_16x16x32_bf16 v[56:59], v[68:71], v[8:11], v[56:59]
	ds_read_b128 v[64:67], v98 offset:51072
	ds_read_b128 v[68:71], v98 offset:51136
	s_waitcnt lgkmcnt(2)
	v_mfma_f32_16x16x32_bf16 v[60:63], v[72:75], v[8:11], v[60:63]
	s_waitcnt lgkmcnt(1)
	v_mfma_f32_16x16x32_bf16 v[56:59], v[64:67], v[4:7], v[56:59]
	ds_read_b128 v[64:67], v98 offset:59520
	ds_read_b128 v[72:75], v98 offset:59584
	s_waitcnt lgkmcnt(1)
	v_mfma_f32_16x16x32_bf16 v[64:67], v[64:67], v[4:7], v[60:63]
	v_mfma_f32_16x16x32_bf16 v[60:63], v[68:71], v[0:3], v[56:59]
	ds_read_b128 v[68:71], v99 offset:64
	s_waitcnt lgkmcnt(1)
	v_mfma_f32_16x16x32_bf16 v[56:59], v[72:75], v[0:3], v[64:67]
	s_nop 3
	ds_read_b128 v[64:67], v99
	ds_read_b128 v[72:75], v108
	ds_read_b128 v[76:79], v108 offset:64
	s_waitcnt lgkmcnt(2)
	v_mfma_f32_16x16x32_bf16 v[64:67], v[64:67], v[28:31], 0
	s_waitcnt lgkmcnt(1)
	v_mfma_f32_16x16x32_bf16 v[72:75], v[72:75], v[28:31], 0
	v_mfma_f32_16x16x32_bf16 v[64:67], v[68:71], v[24:27], v[64:67]
	s_waitcnt lgkmcnt(0)
	v_mfma_f32_16x16x32_bf16 v[68:71], v[76:79], v[24:27], v[72:75]
	s_nop 4
	ds_read_b128 v[72:75], v99 offset:128
	ds_read_b128 v[76:79], v99 offset:192
	s_waitcnt lgkmcnt(1)
	v_mfma_f32_16x16x32_bf16 v[64:67], v[72:75], v[20:23], v[64:67]
	ds_read_b128 v[72:75], v108 offset:128
	ds_read_b128 v[100:103], v108 offset:192
	s_waitcnt lgkmcnt(1)
	v_mfma_f32_16x16x32_bf16 v[68:71], v[72:75], v[20:23], v[68:71]
	v_mfma_f32_16x16x32_bf16 v[64:67], v[76:79], v[16:19], v[64:67]
	ds_read_b128 v[72:75], v99 offset:256
	ds_read_b128 v[76:79], v99 offset:320
	s_waitcnt lgkmcnt(2)
	v_mfma_f32_16x16x32_bf16 v[68:71], v[100:103], v[16:19], v[68:71]
	s_waitcnt lgkmcnt(1)
	v_mfma_f32_16x16x32_bf16 v[64:67], v[72:75], v[12:15], v[64:67]
	ds_read_b128 v[72:75], v108 offset:256
	ds_read_b128 v[100:103], v108 offset:320
	s_waitcnt lgkmcnt(1)
	v_mfma_f32_16x16x32_bf16 v[68:71], v[72:75], v[12:15], v[68:71]
	v_mfma_f32_16x16x32_bf16 v[64:67], v[76:79], v[8:11], v[64:67]
	ds_read_b128 v[72:75], v99 offset:384
	ds_read_b128 v[76:79], v99 offset:448
	v_add_u32_e32 v99, 0x14a00, v98
	s_waitcnt lgkmcnt(2)
	v_mfma_f32_16x16x32_bf16 v[68:71], v[100:103], v[8:11], v[68:71]
	s_waitcnt lgkmcnt(1)
	v_mfma_f32_16x16x32_bf16 v[64:67], v[72:75], v[4:7], v[64:67]
	ds_read_b128 v[72:75], v108 offset:384
	ds_read_b128 v[100:103], v108 offset:448
	s_waitcnt lgkmcnt(1)
	v_mfma_f32_16x16x32_bf16 v[72:75], v[72:75], v[4:7], v[68:71]
	v_mfma_f32_16x16x32_bf16 v[68:71], v[76:79], v[0:3], v[64:67]
	ds_read_b128 v[76:79], v99 offset:64
	s_waitcnt lgkmcnt(1)
	v_mfma_f32_16x16x32_bf16 v[64:67], v[100:103], v[0:3], v[72:75]
	s_nop 3
	ds_read_b128 v[72:75], v99
	ds_read_b128 v[100:103], v120
	ds_read_b128 v[108:111], v120 offset:64
	s_waitcnt lgkmcnt(2)
	v_mfma_f32_16x16x32_bf16 v[72:75], v[72:75], v[28:31], 0
	s_waitcnt lgkmcnt(1)
	v_mfma_f32_16x16x32_bf16 v[100:103], v[100:103], v[28:31], 0
	v_mfma_f32_16x16x32_bf16 v[72:75], v[76:79], v[24:27], v[72:75]
	s_waitcnt lgkmcnt(0)
	v_mfma_f32_16x16x32_bf16 v[76:79], v[108:111], v[24:27], v[100:103]
	s_nop 4
	ds_read_b128 v[100:103], v99 offset:128
	ds_read_b128 v[108:111], v99 offset:192
	s_waitcnt lgkmcnt(1)
	v_mfma_f32_16x16x32_bf16 v[72:75], v[100:103], v[20:23], v[72:75]
	ds_read_b128 v[100:103], v120 offset:128
	ds_read_b128 v[116:119], v120 offset:192
	s_waitcnt lgkmcnt(1)
	v_mfma_f32_16x16x32_bf16 v[76:79], v[100:103], v[20:23], v[76:79]
	v_mfma_f32_16x16x32_bf16 v[72:75], v[108:111], v[16:19], v[72:75]
	ds_read_b128 v[100:103], v99 offset:256
	ds_read_b128 v[108:111], v99 offset:320
	s_waitcnt lgkmcnt(2)
	v_mfma_f32_16x16x32_bf16 v[76:79], v[116:119], v[16:19], v[76:79]
	s_waitcnt lgkmcnt(1)
	v_mfma_f32_16x16x32_bf16 v[72:75], v[100:103], v[12:15], v[72:75]
	ds_read_b128 v[100:103], v120 offset:256
	ds_read_b128 v[116:119], v120 offset:320
	s_waitcnt lgkmcnt(1)
	v_mfma_f32_16x16x32_bf16 v[76:79], v[100:103], v[12:15], v[76:79]
	v_mfma_f32_16x16x32_bf16 v[72:75], v[108:111], v[8:11], v[72:75]
	ds_read_b128 v[100:103], v99 offset:384
	ds_read_b128 v[108:111], v99 offset:448
	v_add_u32_e32 v99, 0x18c00, v98
	s_waitcnt lgkmcnt(2)
	v_mfma_f32_16x16x32_bf16 v[76:79], v[116:119], v[8:11], v[76:79]
	s_waitcnt lgkmcnt(1)
	v_mfma_f32_16x16x32_bf16 v[72:75], v[100:103], v[4:7], v[72:75]
	ds_read_b128 v[100:103], v120 offset:384
	ds_read_b128 v[116:119], v120 offset:448
	s_waitcnt lgkmcnt(1)
	v_mfma_f32_16x16x32_bf16 v[100:103], v[100:103], v[4:7], v[76:79]
	v_mfma_f32_16x16x32_bf16 v[76:79], v[108:111], v[0:3], v[72:75]
	ds_read_b128 v[108:111], v99 offset:64
	s_waitcnt lgkmcnt(1)
	v_mfma_f32_16x16x32_bf16 v[72:75], v[116:119], v[0:3], v[100:103]
	s_nop 3
	ds_read_b128 v[100:103], v99
	ds_read_b128 v[116:119], v136
	ds_read_b128 v[120:123], v136 offset:64
	s_waitcnt lgkmcnt(2)
	v_mfma_f32_16x16x32_bf16 v[100:103], v[100:103], v[28:31], 0
	s_waitcnt lgkmcnt(1)
	v_mfma_f32_16x16x32_bf16 v[116:119], v[116:119], v[28:31], 0
	v_mfma_f32_16x16x32_bf16 v[100:103], v[108:111], v[24:27], v[100:103]
	s_waitcnt lgkmcnt(0)
	v_mfma_f32_16x16x32_bf16 v[108:111], v[120:123], v[24:27], v[116:119]
	s_nop 4
	ds_read_b128 v[116:119], v99 offset:128
	ds_read_b128 v[120:123], v99 offset:192
	s_waitcnt lgkmcnt(1)
	v_mfma_f32_16x16x32_bf16 v[100:103], v[116:119], v[20:23], v[100:103]
	ds_read_b128 v[116:119], v136 offset:128
	ds_read_b128 v[128:131], v136 offset:192
	s_waitcnt lgkmcnt(1)
	v_mfma_f32_16x16x32_bf16 v[108:111], v[116:119], v[20:23], v[108:111]
	v_mfma_f32_16x16x32_bf16 v[100:103], v[120:123], v[16:19], v[100:103]
	ds_read_b128 v[116:119], v99 offset:256
	ds_read_b128 v[120:123], v99 offset:320
	s_waitcnt lgkmcnt(2)
	v_mfma_f32_16x16x32_bf16 v[108:111], v[128:131], v[16:19], v[108:111]
	s_waitcnt lgkmcnt(1)
	v_mfma_f32_16x16x32_bf16 v[100:103], v[116:119], v[12:15], v[100:103]
	ds_read_b128 v[116:119], v136 offset:256
	ds_read_b128 v[128:131], v136 offset:320
	s_waitcnt lgkmcnt(1)
	v_mfma_f32_16x16x32_bf16 v[108:111], v[116:119], v[12:15], v[108:111]
	v_mfma_f32_16x16x32_bf16 v[100:103], v[120:123], v[8:11], v[100:103]
	ds_read_b128 v[116:119], v99 offset:384
	ds_read_b128 v[120:123], v99 offset:448
	v_add_u32_e32 v99, 0x1ce00, v98
	v_add_u32_e32 v98, 0x1ef00, v98
	s_waitcnt lgkmcnt(2)
	v_mfma_f32_16x16x32_bf16 v[108:111], v[128:131], v[8:11], v[108:111]
	s_waitcnt lgkmcnt(1)
	v_mfma_f32_16x16x32_bf16 v[100:103], v[116:119], v[4:7], v[100:103]
	ds_read_b128 v[116:119], v136 offset:384
	ds_read_b128 v[128:131], v136 offset:448
	s_waitcnt lgkmcnt(1)
	v_mfma_f32_16x16x32_bf16 v[108:111], v[116:119], v[4:7], v[108:111]
	ds_read_b128 v[116:119], v99 offset:64
	v_mfma_f32_16x16x32_bf16 v[120:123], v[120:123], v[0:3], v[100:103]
	s_waitcnt lgkmcnt(1)
	v_mfma_f32_16x16x32_bf16 v[100:103], v[128:131], v[0:3], v[108:111]
	s_nop 3
	ds_read_b128 v[108:111], v99
	ds_read_b128 v[128:131], v98
	ds_read_b128 v[136:139], v98 offset:64
	s_waitcnt lgkmcnt(2)
	v_mfma_f32_16x16x32_bf16 v[108:111], v[108:111], v[28:31], 0
	s_waitcnt lgkmcnt(1)
	v_mfma_f32_16x16x32_bf16 v[28:31], v[128:131], v[28:31], 0
	v_mfma_f32_16x16x32_bf16 v[108:111], v[116:119], v[24:27], v[108:111]
	s_waitcnt lgkmcnt(0)
	v_mfma_f32_16x16x32_bf16 v[24:27], v[136:139], v[24:27], v[28:31]
	s_nop 4
	ds_read_b128 v[28:31], v99 offset:128
	ds_read_b128 v[116:119], v99 offset:192
	s_waitcnt lgkmcnt(1)
	v_mfma_f32_16x16x32_bf16 v[28:31], v[28:31], v[20:23], v[108:111]
	s_nop 2
	ds_read_b128 v[108:111], v98 offset:128
	ds_read_b128 v[128:131], v98 offset:192
	s_waitcnt lgkmcnt(1)
	v_mfma_f32_16x16x32_bf16 v[20:23], v[108:111], v[20:23], v[24:27]
	v_mfma_f32_16x16x32_bf16 v[24:27], v[116:119], v[16:19], v[28:31]
	s_nop 2
	ds_read_b128 v[28:31], v99 offset:256
	s_waitcnt lgkmcnt(1)
	v_mfma_f32_16x16x32_bf16 v[16:19], v[128:131], v[16:19], v[20:23]
	s_nop 2
	ds_read_b128 v[20:23], v98 offset:256
	ds_read_b128 v[108:111], v99 offset:320
	ds_read_b128 v[116:119], v98 offset:320
	s_waitcnt lgkmcnt(3)
	v_mfma_f32_16x16x32_bf16 v[24:27], v[28:31], v[12:15], v[24:27]
	ds_read_b128 v[28:31], v99 offset:384
	ds_read_b128 v[128:131], v99 offset:448
	ds_read_b128 v[136:139], v98 offset:384
	ds_read_b128 v[176:179], v98 offset:448
	s_waitcnt lgkmcnt(6)
	v_mfma_f32_16x16x32_bf16 v[12:15], v[20:23], v[12:15], v[16:19]
	s_waitcnt lgkmcnt(5)
	v_mfma_f32_16x16x32_bf16 v[24:27], v[108:111], v[8:11], v[24:27]
	s_nop 0
	v_lshl_add_u64 v[16:17], s[0:1], 0, v[80:81]
	s_mov_b64 s[0:1], 0x6c00000
	v_lshl_add_u64 v[180:181], v[16:17], 0, s[0:1]
	s_waitcnt lgkmcnt(4)
	v_mfma_f32_16x16x32_bf16 v[8:11], v[116:119], v[8:11], v[12:15]
	v_lshl_add_u64 v[16:17], v[180:181], 0, v[82:83]
	v_lshl_add_u64 v[20:21], v[180:181], 0, v[84:85]
	v_lshl_add_u64 v[80:81], v[180:181], 0, v[86:87]
	s_waitcnt lgkmcnt(3)
	v_mfma_f32_16x16x32_bf16 v[12:15], v[28:31], v[4:7], v[24:27]
	v_lshl_add_u64 v[82:83], v[180:181], 0, v[88:89]
	global_load_dwordx4 v[16:19], v[16:17], off
	s_nop 0
	global_load_dwordx4 v[20:23], v[20:21], off
	v_lshl_add_u64 v[24:25], v[180:181], 0, v[90:91]
	s_waitcnt lgkmcnt(0)
	v_mfma_f32_16x16x32_bf16 v[8:11], v[136:139], v[4:7], v[8:11]
	global_load_dwordx4 v[28:31], v[80:81], off
	s_nop 0
	global_load_dwordx4 v[80:83], v[82:83], off
	v_lshl_add_u64 v[26:27], v[180:181], 0, v[92:93]
	global_load_dwordx4 v[84:87], v[24:25], off
	global_load_dwordx4 v[88:91], v[26:27], off
	v_lshl_add_u64 v[24:25], v[180:181], 0, v[94:95]
	v_mfma_f32_16x16x32_bf16 v[4:7], v[128:131], v[0:3], v[12:15]
	v_lshl_add_u64 v[26:27], v[180:181], 0, v[96:97]
	global_load_dwordx4 v[92:95], v[24:25], off
	global_load_dwordx4 v[96:99], v[26:27], off
	v_lshl_add_u64 v[12:13], v[180:181], 0, v[104:105]
	v_mfma_f32_16x16x32_bf16 v[0:3], v[176:179], v[0:3], v[8:11]
	s_mov_b64 s[0:1], s[42:43]
	s_nop 1
	v_lshl_add_u64 v[8:9], v[180:181], 0, v[106:107]
	global_load_dwordx4 v[104:107], v[12:13], off
	global_load_dwordx4 v[108:111], v[8:9], off
	v_lshl_add_u64 v[8:9], v[180:181], 0, v[112:113]
	v_lshl_add_u64 v[10:11], v[180:181], 0, v[114:115]
	global_load_dwordx4 v[112:115], v[8:9], off
	global_load_dwordx4 v[116:119], v[10:11], off
	v_max_f32_e32 v8, v38, v38
	v_max_f32_e32 v9, v37, v37
	v_max_f32_e32 v8, v9, v8
	v_max3_f32 v8, v36, s33, v8
	v_max_f32_e32 v9, v34, v34
	v_max_f32_e32 v10, v33, v33
	v_max3_f32 v8, v8, v39, v32
	v_max_f32_e32 v9, v10, v9
	v_max3_f32 v8, v8, v9, v35
	v_max_f32_e32 v9, v46, v46
	v_max_f32_e32 v10, v45, v45
	v_max_f32_e32 v9, v10, v9
	v_max3_f32 v8, v8, v44, v9
	v_max_f32_e32 v9, v42, v42
	v_max_f32_e32 v10, v41, v41
	v_max3_f32 v8, v8, v47, v40
	v_max_f32_e32 v9, v10, v9
	v_max3_f32 v8, v8, v9, v43
	v_max_f32_e32 v9, v54, v54
	v_max_f32_e32 v10, v53, v53
	v_max_f32_e32 v9, v10, v9
	v_max3_f32 v8, v8, v52, v9
	v_max_f32_e32 v9, v50, v50
	v_max_f32_e32 v10, v49, v49
	v_max3_f32 v8, v8, v55, v48
	v_max_f32_e32 v9, v10, v9
	v_max3_f32 v8, v8, v9, v51
	v_max_f32_e32 v9, v62, v62
	v_max_f32_e32 v10, v61, v61
	v_max_f32_e32 v9, v10, v9
	v_max3_f32 v8, v8, v60, v9
	v_max_f32_e32 v9, v58, v58
	v_max_f32_e32 v10, v57, v57
	v_max3_f32 v8, v8, v63, v56
	v_max_f32_e32 v9, v10, v9
	v_max3_f32 v8, v8, v9, v59
	v_max_f32_e32 v9, v70, v70
	v_max_f32_e32 v10, v69, v69
	v_max_f32_e32 v9, v10, v9
	v_max3_f32 v8, v8, v68, v9
	v_max_f32_e32 v9, v66, v66
	v_max_f32_e32 v10, v65, v65
	v_max3_f32 v8, v8, v71, v64
	v_max_f32_e32 v9, v10, v9
	v_max3_f32 v8, v8, v9, v67
	v_max_f32_e32 v9, v78, v78
	v_max_f32_e32 v10, v77, v77
	v_max_f32_e32 v9, v10, v9
	v_max3_f32 v8, v8, v76, v9
	v_max_f32_e32 v9, v74, v74
	v_max_f32_e32 v10, v73, v73
	v_max3_f32 v8, v8, v79, v72
	v_max_f32_e32 v9, v10, v9
	v_max3_f32 v8, v8, v9, v75
	v_max_f32_e32 v9, v122, v122
	v_max_f32_e32 v10, v121, v121
	v_max_f32_e32 v9, v10, v9
	v_max3_f32 v8, v8, v120, v9
	v_max_f32_e32 v9, v102, v102
	v_max_f32_e32 v10, v101, v101
	v_max3_f32 v8, v8, v123, v100
	v_max_f32_e32 v9, v10, v9
	v_max3_f32 v8, v8, v9, v103
	v_max_f32_e32 v9, v6, v6
	v_max_f32_e32 v10, v5, v5
	v_max_f32_e32 v9, v10, v9
	v_max3_f32 v8, v8, v4, v9
	v_max_f32_e32 v9, v2, v2
	v_max_f32_e32 v10, v1, v1
	v_max3_f32 v8, v8, v7, v0
	v_max_f32_e32 v9, v10, v9
	v_max3_f32 v12, v8, v9, v3
	v_cndmask_b32_e32 v8, v217, v223, vcc
	v_lshlrev_b32_e32 v13, 2, v8
	ds_bpermute_b32 v14, v13, v12
	v_lshl_add_u64 v[8:9], v[180:181], 0, v[124:125]
	v_lshl_add_u64 v[10:11], v[180:181], 0, v[126:127]
	global_load_dwordx4 v[124:127], v[8:9], off
	global_load_dwordx4 v[128:131], v[10:11], off
	v_cmp_lt_i32_e32 vcc, v224, v218
	s_waitcnt lgkmcnt(0)
	v_max_f32_e32 v8, v14, v14
	v_max_f32_e32 v12, v12, v8
	v_cndmask_b32_e32 v8, v217, v224, vcc
	v_lshlrev_b32_e32 v14, 2, v8
	ds_bpermute_b32 v15, v14, v12
	v_lshl_add_u64 v[8:9], v[180:181], 0, v[132:133]
	v_lshl_add_u64 v[10:11], v[180:181], 0, v[134:135]
	global_load_dwordx4 v[132:135], v[8:9], off
	global_load_dwordx4 v[136:139], v[10:11], off
	s_waitcnt lgkmcnt(0)
	v_max_f32_e32 v8, v15, v15
	v_max_f32_e32 v8, v12, v8
	v_sub_f32_e32 v9, v36, v8
	v_exp_f32_e32 v9, v9
	v_sub_f32_e32 v10, v37, v8
	v_exp_f32_e32 v10, v10
	v_sub_f32_e32 v11, v38, v8
	v_exp_f32_e32 v11, v11
	v_sub_f32_e32 v12, v39, v8
	v_exp_f32_e32 v12, v12
	v_sub_f32_e32 v24, v32, v8
	v_add_f32_e32 v15, 0, v9
	v_exp_f32_e32 v24, v24
	v_sub_f32_e32 v25, v33, v8
	v_add_f32_e32 v15, v10, v15
	v_exp_f32_e32 v25, v25
	v_sub_f32_e32 v26, v34, v8
	v_add_f32_e32 v15, v11, v15
	v_exp_f32_e32 v26, v26
	v_sub_f32_e32 v27, v35, v8
	v_add_f32_e32 v15, v12, v15
	v_exp_f32_e32 v27, v27
	v_sub_f32_e32 v32, v44, v8
	v_add_f32_e32 v15, v24, v15
	v_exp_f32_e32 v32, v32
	v_sub_f32_e32 v33, v45, v8
	v_add_f32_e32 v15, v25, v15
	v_exp_f32_e32 v33, v33
	v_sub_f32_e32 v34, v46, v8
	v_add_f32_e32 v15, v26, v15
	v_exp_f32_e32 v34, v34
	v_sub_f32_e32 v35, v47, v8
	v_add_f32_e32 v15, v27, v15
	v_exp_f32_e32 v35, v35
	v_sub_f32_e32 v36, v40, v8
	v_add_f32_e32 v15, v32, v15
	v_exp_f32_e32 v36, v36
	v_sub_f32_e32 v37, v41, v8
	v_add_f32_e32 v15, v33, v15
	v_exp_f32_e32 v37, v37
	v_sub_f32_e32 v38, v42, v8
	v_add_f32_e32 v15, v34, v15
	v_exp_f32_e32 v38, v38
	v_sub_f32_e32 v39, v43, v8
	v_add_f32_e32 v15, v35, v15
	v_exp_f32_e32 v39, v39
	v_sub_f32_e32 v40, v52, v8
	v_add_f32_e32 v15, v36, v15
	v_exp_f32_e32 v40, v40
	v_sub_f32_e32 v41, v53, v8
	v_add_f32_e32 v15, v37, v15
	v_exp_f32_e32 v41, v41
	v_sub_f32_e32 v42, v54, v8
	v_add_f32_e32 v15, v38, v15
	v_exp_f32_e32 v42, v42
	v_sub_f32_e32 v43, v55, v8
	v_add_f32_e32 v15, v39, v15
	v_exp_f32_e32 v43, v43
	v_sub_f32_e32 v44, v48, v8
	v_add_f32_e32 v15, v40, v15
	v_exp_f32_e32 v44, v44
	v_sub_f32_e32 v45, v49, v8
	v_add_f32_e32 v15, v41, v15
	v_exp_f32_e32 v45, v45
	v_sub_f32_e32 v46, v50, v8
	v_add_f32_e32 v15, v42, v15
	v_exp_f32_e32 v46, v46
	v_sub_f32_e32 v47, v51, v8
	v_add_f32_e32 v15, v43, v15
	v_exp_f32_e32 v47, v47
	v_sub_f32_e32 v48, v60, v8
	v_add_f32_e32 v15, v44, v15
	v_exp_f32_e32 v48, v48
	v_sub_f32_e32 v49, v61, v8
	v_add_f32_e32 v15, v45, v15
	v_exp_f32_e32 v49, v49
	v_sub_f32_e32 v50, v62, v8
	v_add_f32_e32 v15, v46, v15
	v_exp_f32_e32 v50, v50
	v_sub_f32_e32 v51, v63, v8
	v_add_f32_e32 v15, v47, v15
	v_exp_f32_e32 v51, v51
	v_sub_f32_e32 v52, v56, v8
	v_add_f32_e32 v15, v48, v15
	v_exp_f32_e32 v52, v52
	v_sub_f32_e32 v53, v57, v8
	v_add_f32_e32 v15, v49, v15
	v_exp_f32_e32 v53, v53
	v_sub_f32_e32 v54, v58, v8
	v_add_f32_e32 v15, v50, v15
	v_exp_f32_e32 v54, v54
	v_sub_f32_e32 v55, v59, v8
	v_add_f32_e32 v15, v51, v15
	v_exp_f32_e32 v55, v55
	v_sub_f32_e32 v56, v68, v8
	v_add_f32_e32 v15, v52, v15
	v_exp_f32_e32 v56, v56
	v_sub_f32_e32 v57, v69, v8
	v_add_f32_e32 v15, v53, v15
	v_exp_f32_e32 v57, v57
	v_sub_f32_e32 v58, v70, v8
	v_add_f32_e32 v15, v54, v15
	v_exp_f32_e32 v58, v58
	v_sub_f32_e32 v59, v71, v8
	v_add_f32_e32 v15, v55, v15
	v_exp_f32_e32 v59, v59
	v_sub_f32_e32 v60, v64, v8
	v_add_f32_e32 v15, v56, v15
	v_exp_f32_e32 v60, v60
	v_sub_f32_e32 v61, v65, v8
	v_add_f32_e32 v15, v57, v15
	v_exp_f32_e32 v61, v61
	v_sub_f32_e32 v62, v66, v8
	v_add_f32_e32 v15, v58, v15
	v_exp_f32_e32 v62, v62
	v_sub_f32_e32 v63, v67, v8
	v_add_f32_e32 v15, v59, v15
	v_exp_f32_e32 v63, v63
	v_sub_f32_e32 v64, v76, v8
	v_add_f32_e32 v15, v60, v15
	v_exp_f32_e32 v64, v64
	v_sub_f32_e32 v65, v77, v8
	v_add_f32_e32 v15, v61, v15
	v_exp_f32_e32 v65, v65
	v_sub_f32_e32 v66, v78, v8
	v_add_f32_e32 v15, v62, v15
	v_exp_f32_e32 v66, v66
	v_sub_f32_e32 v67, v79, v8
	v_add_f32_e32 v15, v63, v15
	v_exp_f32_e32 v67, v67
	v_sub_f32_e32 v68, v72, v8
	v_add_f32_e32 v15, v64, v15
	v_exp_f32_e32 v68, v68
	v_sub_f32_e32 v69, v73, v8
	v_add_f32_e32 v15, v65, v15
	v_exp_f32_e32 v69, v69
	v_sub_f32_e32 v70, v74, v8
	v_add_f32_e32 v15, v66, v15
	v_exp_f32_e32 v70, v70
	v_sub_f32_e32 v71, v75, v8
	v_add_f32_e32 v15, v67, v15
	v_exp_f32_e32 v71, v71
	v_sub_f32_e32 v72, v120, v8
	v_add_f32_e32 v15, v68, v15
	v_exp_f32_e32 v72, v72
	v_sub_f32_e32 v73, v121, v8
	v_add_f32_e32 v15, v69, v15
	v_exp_f32_e32 v73, v73
	v_sub_f32_e32 v74, v122, v8
	v_add_f32_e32 v15, v70, v15
	v_exp_f32_e32 v74, v74
	v_sub_f32_e32 v75, v123, v8
	v_add_f32_e32 v15, v71, v15
	v_exp_f32_e32 v75, v75
	v_sub_f32_e32 v76, v100, v8
	v_add_f32_e32 v15, v72, v15
	v_exp_f32_e32 v76, v76
	v_sub_f32_e32 v77, v101, v8
	v_add_f32_e32 v15, v73, v15
	v_exp_f32_e32 v77, v77
	v_sub_f32_e32 v78, v102, v8
	v_add_f32_e32 v15, v74, v15
	v_exp_f32_e32 v78, v78
	v_sub_f32_e32 v79, v103, v8
	v_add_f32_e32 v15, v75, v15
	v_exp_f32_e32 v79, v79
	v_sub_f32_e32 v4, v4, v8
	v_add_f32_e32 v15, v76, v15
	v_exp_f32_e32 v100, v4
	v_sub_f32_e32 v4, v5, v8
	v_add_f32_e32 v15, v77, v15
	v_exp_f32_e32 v101, v4
	v_sub_f32_e32 v4, v6, v8
	v_add_f32_e32 v15, v78, v15
	v_exp_f32_e32 v102, v4
	v_sub_f32_e32 v4, v7, v8
	v_add_f32_e32 v15, v79, v15
	v_exp_f32_e32 v103, v4
	v_sub_f32_e32 v0, v0, v8
	v_add_f32_e32 v4, v100, v15
	v_exp_f32_e32 v120, v0
	v_sub_f32_e32 v0, v1, v8
	v_add_f32_e32 v4, v101, v4
	v_exp_f32_e32 v121, v0
	v_sub_f32_e32 v0, v2, v8
	v_add_f32_e32 v4, v102, v4
	v_exp_f32_e32 v122, v0
	v_sub_f32_e32 v0, v3, v8
	v_add_f32_e32 v4, v103, v4
	v_exp_f32_e32 v123, v0
	v_add_f32_e32 v0, v120, v4
	v_add_f32_e32 v0, v121, v0
	v_add_f32_e32 v0, v122, v0
	v_add_f32_e32 v0, v123, v0
	ds_bpermute_b32 v1, v13, v0
	s_barrier
	s_waitcnt vmcnt(0) lgkmcnt(0)
	ds_write_b128 v142, v[16:19]
	ds_write_b128 v144, v[20:23]
	ds_write_b128 v146, v[28:31]
	ds_write_b128 v148, v[80:83]
	ds_write_b128 v150, v[84:87]
	ds_write_b128 v152, v[88:91]
	ds_write_b128 v154, v[92:95]
	ds_write_b128 v156, v[96:99]
	ds_write_b128 v158, v[104:107]
	ds_write_b128 v160, v[108:111]
	ds_write_b128 v162, v[112:115]
	ds_write_b128 v164, v[116:119]
	ds_write_b128 v166, v[124:127]
	ds_write_b128 v168, v[128:131]
	ds_write_b128 v170, v[132:135]
	ds_write_b128 v172, v[136:139]
	s_waitcnt lgkmcnt(0)
	v_add_f32_e32 v0, v0, v1
	ds_bpermute_b32 v1, v14, v0
	s_barrier
	s_waitcnt lgkmcnt(0)
	v_cvt_pk_bf16_f32 v2, v24, v25
	v_add_f32_e32 v145, v0, v1
	v_rcp_f32_e32 v16, v145
	v_lshl_add_u64 v[18:19], s[0:1], 0, v[140:141]
	v_lshl_add_u64 v[18:19], v[18:19], 0, s[82:83]
	v_lshl_add_u64 v[18:19], v[18:19], 0, v[192:193]
	s_mov_b64 s[0:1], 0x11e00000
	v_cvt_pk_bf16_f32 v0, v9, v10
	v_cvt_pk_bf16_f32 v1, v11, v12
	v_cvt_pk_bf16_f32 v3, v26, v27
	v_cvt_pk_bf16_f32 v4, v32, v33
	v_cvt_pk_bf16_f32 v5, v34, v35
	v_cvt_pk_bf16_f32 v6, v36, v37
	v_cvt_pk_bf16_f32 v7, v38, v39
	v_cvt_pk_bf16_f32 v8, v40, v41
	v_cvt_pk_bf16_f32 v9, v42, v43
	v_cvt_pk_bf16_f32 v10, v44, v45
	v_cvt_pk_bf16_f32 v11, v46, v47
	v_cvt_pk_bf16_f32 v12, v48, v49
	v_cvt_pk_bf16_f32 v13, v50, v51
	v_cvt_pk_bf16_f32 v14, v52, v53
	v_cvt_pk_bf16_f32 v15, v54, v55
	v_cvt_pk_bf16_f32 v24, v56, v57
	v_cvt_pk_bf16_f32 v25, v58, v59
	v_cvt_pk_bf16_f32 v26, v60, v61
	v_cvt_pk_bf16_f32 v27, v62, v63
	v_cvt_pk_bf16_f32 v32, v64, v65
	v_cvt_pk_bf16_f32 v33, v66, v67
	v_cvt_pk_bf16_f32 v34, v68, v69
	v_cvt_pk_bf16_f32 v35, v70, v71
	v_cvt_pk_bf16_f32 v36, v72, v73
	v_cvt_pk_bf16_f32 v37, v74, v75
	v_cvt_pk_bf16_f32 v38, v76, v77
	v_cvt_pk_bf16_f32 v39, v78, v79
	v_cvt_pk_bf16_f32 v40, v100, v101
	v_cvt_pk_bf16_f32 v41, v102, v103
	v_cvt_pk_bf16_f32 v42, v120, v121
	v_cvt_pk_bf16_f32 v43, v122, v123
	v_lshl_add_u64 v[18:19], v[18:19], 0, s[0:1]
	v_mov_b32_e32 v17, v16
	v_add3_u32 v20, v143, v192, 0
	s_mov_b32 s0, -2
	ds_read_b64 v[104:105], v20
	ds_read_b64 v[106:107], v20 offset:32
	ds_read_b64 v[108:109], v20 offset:64
	ds_read_b64 v[110:111], v20 offset:96
	ds_read_b64 v[112:113], v20 offset:128
	ds_read_b64 v[114:115], v20 offset:160
	ds_read_b64 v[116:117], v20 offset:192
	ds_read_b64 v[118:119], v20 offset:224
	ds_read_b64 v[120:121], v20 offset:256
	ds_read_b64 v[122:123], v20 offset:288
	ds_read_b64 v[124:125], v20 offset:320
	ds_read_b64 v[126:127], v20 offset:352
	ds_read_b64 v[128:129], v20 offset:384
	ds_read_b64 v[130:131], v20 offset:416
	ds_read_b64 v[132:133], v20 offset:448
	ds_read_b64 v[134:135], v20 offset:480
	v_add_u32_e32 v20, 0x2100, v20
	s_mov_b32 s0, 0
.LBB0_47:
	ds_read_b64 v[84:85], v20
	ds_read_b64 v[86:87], v20 offset:32
	ds_read_b64 v[88:89], v20 offset:64
	ds_read_b64 v[90:91], v20 offset:96
	ds_read_b64 v[92:93], v20 offset:128
	ds_read_b64 v[94:95], v20 offset:160
	ds_read_b64 v[60:61], v20 offset:192
	ds_read_b64 v[62:63], v20 offset:224
	ds_read_b64 v[64:65], v20 offset:256
	ds_read_b64 v[66:67], v20 offset:288
	ds_read_b64 v[72:73], v20 offset:320
	ds_read_b64 v[74:75], v20 offset:352
	ds_read_b64 v[176:177], v20 offset:384
	ds_read_b64 v[178:179], v20 offset:416
	ds_read_b64 v[180:181], v20 offset:448
	ds_read_b64 v[182:183], v20 offset:480
	v_add_u32_e32 v20, 0x2100, v20
	s_waitcnt lgkmcnt(15)
	v_mfma_f32_16x16x32_bf16 v[28:31], v[104:107], v[0:3], 0
	v_mfma_f32_16x16x32_bf16 v[28:31], v[108:111], v[4:7], v[28:31]
	v_mfma_f32_16x16x32_bf16 v[28:31], v[112:115], v[8:11], v[28:31]
	v_mfma_f32_16x16x32_bf16 v[28:31], v[116:119], v[12:15], v[28:31]
	v_mfma_f32_16x16x32_bf16 v[28:31], v[120:123], v[24:27], v[28:31]
	v_mfma_f32_16x16x32_bf16 v[28:31], v[124:127], v[32:35], v[28:31]
	v_mfma_f32_16x16x32_bf16 v[28:31], v[128:131], v[36:39], v[28:31]
	v_mfma_f32_16x16x32_bf16 v[28:31], v[132:135], v[40:43], v[28:31]
	ds_read_b64 v[104:105], v20
	ds_read_b64 v[106:107], v20 offset:32
	ds_read_b64 v[108:109], v20 offset:64
	ds_read_b64 v[110:111], v20 offset:96
	ds_read_b64 v[112:113], v20 offset:128
	ds_read_b64 v[114:115], v20 offset:160
	ds_read_b64 v[116:117], v20 offset:192
	ds_read_b64 v[118:119], v20 offset:224
	ds_read_b64 v[120:121], v20 offset:256
	ds_read_b64 v[122:123], v20 offset:288
	ds_read_b64 v[124:125], v20 offset:320
	ds_read_b64 v[126:127], v20 offset:352
	ds_read_b64 v[128:129], v20 offset:384
	ds_read_b64 v[130:131], v20 offset:416
	ds_read_b64 v[132:133], v20 offset:448
	ds_read_b64 v[134:135], v20 offset:480
	v_add_u32_e32 v20, 0x2100, v20
	s_waitcnt lgkmcnt(15)
	v_mfma_f32_16x16x32_bf16 v[44:47], v[84:87], v[0:3], 0
	v_mfma_f32_16x16x32_bf16 v[44:47], v[88:91], v[4:7], v[44:47]
	v_mfma_f32_16x16x32_bf16 v[44:47], v[92:95], v[8:11], v[44:47]
	v_mfma_f32_16x16x32_bf16 v[44:47], v[60:63], v[12:15], v[44:47]
	v_mfma_f32_16x16x32_bf16 v[44:47], v[64:67], v[24:27], v[44:47]
	v_mfma_f32_16x16x32_bf16 v[44:47], v[72:75], v[32:35], v[44:47]
	v_mfma_f32_16x16x32_bf16 v[44:47], v[176:179], v[36:39], v[44:47]
	v_mfma_f32_16x16x32_bf16 v[44:47], v[180:183], v[40:43], v[44:47]
	v_pk_mul_f32 v[22:23], v[16:17], v[28:29]
	v_pk_mul_f32 v[48:49], v[16:17], v[30:31]
	v_cvt_pk_bf16_f32 v22, v22, v23
	v_cvt_pk_bf16_f32 v23, v48, v49
	global_store_dwordx2 v[18:19], v[22:23], off
	s_nop 3
	v_pk_mul_f32 v[50:51], v[16:17], v[44:45]
	v_pk_mul_f32 v[52:53], v[16:17], v[46:47]
	v_cvt_pk_bf16_f32 v50, v50, v51
	v_cvt_pk_bf16_f32 v51, v52, v53
	global_store_dwordx2 v[18:19], v[50:51], off offset:32
	ds_read_b64 v[84:85], v20
	ds_read_b64 v[86:87], v20 offset:32
	ds_read_b64 v[88:89], v20 offset:64
	ds_read_b64 v[90:91], v20 offset:96
	ds_read_b64 v[92:93], v20 offset:128
	ds_read_b64 v[94:95], v20 offset:160
	ds_read_b64 v[60:61], v20 offset:192
	ds_read_b64 v[62:63], v20 offset:224
	ds_read_b64 v[64:65], v20 offset:256
	ds_read_b64 v[66:67], v20 offset:288
	ds_read_b64 v[72:73], v20 offset:320
	ds_read_b64 v[74:75], v20 offset:352
	ds_read_b64 v[176:177], v20 offset:384
	ds_read_b64 v[178:179], v20 offset:416
	ds_read_b64 v[180:181], v20 offset:448
	ds_read_b64 v[182:183], v20 offset:480
	v_add_u32_e32 v20, 0x2100, v20
	s_waitcnt lgkmcnt(15)
	v_mfma_f32_16x16x32_bf16 v[28:31], v[104:107], v[0:3], 0
	v_mfma_f32_16x16x32_bf16 v[28:31], v[108:111], v[4:7], v[28:31]
	v_mfma_f32_16x16x32_bf16 v[28:31], v[112:115], v[8:11], v[28:31]
	v_mfma_f32_16x16x32_bf16 v[28:31], v[116:119], v[12:15], v[28:31]
	v_mfma_f32_16x16x32_bf16 v[28:31], v[120:123], v[24:27], v[28:31]
	v_mfma_f32_16x16x32_bf16 v[28:31], v[124:127], v[32:35], v[28:31]
	v_mfma_f32_16x16x32_bf16 v[28:31], v[128:131], v[36:39], v[28:31]
	v_mfma_f32_16x16x32_bf16 v[28:31], v[132:135], v[40:43], v[28:31]
	s_cmp_eq_u32 s0, 3
	s_cbranch_scc1 .Lpv_last
	ds_read_b64 v[104:105], v20
	ds_read_b64 v[106:107], v20 offset:32
	ds_read_b64 v[108:109], v20 offset:64
	ds_read_b64 v[110:111], v20 offset:96
	ds_read_b64 v[112:113], v20 offset:128
	ds_read_b64 v[114:115], v20 offset:160
	ds_read_b64 v[116:117], v20 offset:192
	ds_read_b64 v[118:119], v20 offset:224
	ds_read_b64 v[120:121], v20 offset:256
	ds_read_b64 v[122:123], v20 offset:288
	ds_read_b64 v[124:125], v20 offset:320
	ds_read_b64 v[126:127], v20 offset:352
	ds_read_b64 v[128:129], v20 offset:384
	ds_read_b64 v[130:131], v20 offset:416
	ds_read_b64 v[132:133], v20 offset:448
	ds_read_b64 v[134:135], v20 offset:480
	v_add_u32_e32 v20, 0x2100, v20
	s_waitcnt lgkmcnt(15)
	s_branch .Lpv_b2

.Lpv_b2:
	v_mfma_f32_16x16x32_bf16 v[44:47], v[84:87], v[0:3], 0
	v_mfma_f32_16x16x32_bf16 v[44:47], v[88:91], v[4:7], v[44:47]
	v_mfma_f32_16x16x32_bf16 v[44:47], v[92:95], v[8:11], v[44:47]
	v_mfma_f32_16x16x32_bf16 v[44:47], v[60:63], v[12:15], v[44:47]
	v_mfma_f32_16x16x32_bf16 v[44:47], v[64:67], v[24:27], v[44:47]
	v_mfma_f32_16x16x32_bf16 v[44:47], v[72:75], v[32:35], v[44:47]
	v_mfma_f32_16x16x32_bf16 v[44:47], v[176:179], v[36:39], v[44:47]
	v_mfma_f32_16x16x32_bf16 v[44:47], v[180:183], v[40:43], v[44:47]
	v_pk_mul_f32 v[22:23], v[16:17], v[28:29]
	v_pk_mul_f32 v[48:49], v[16:17], v[30:31]
	v_cvt_pk_bf16_f32 v22, v22, v23
	v_cvt_pk_bf16_f32 v23, v48, v49
	global_store_dwordx2 v[18:19], v[22:23], off offset:64
	s_nop 3
	v_pk_mul_f32 v[50:51], v[16:17], v[44:45]
	v_pk_mul_f32 v[52:53], v[16:17], v[46:47]
	v_cvt_pk_bf16_f32 v50, v50, v51
	v_cvt_pk_bf16_f32 v51, v52, v53
	global_store_dwordx2 v[18:19], v[50:51], off offset:96
	v_lshl_add_u64 v[18:19], v[18:19], 0, s[46:47]
	s_add_i32 s0, s0, 1
	s_cmp_lt_u32 s0, 4
	s_cbranch_scc1 .LBB0_47
	s_add_i32 s16, s16, s70
	s_cmpk_gt_i32 s16, 0x1ff
	s_waitcnt lgkmcnt(0)
	s_barrier
	s_cbranch_scc0 .LBB0_46
	s_branch .LBB0_40

.LBB0_116:
	global_load_dwordx4 v[104:107], v[32:33], off
	global_load_dwordx4 v[108:111], v[32:33], off offset:64
	global_load_dwordx4 v[112:115], v[32:33], off offset:128
	global_load_dwordx4 v[116:119], v[32:33], off offset:192
	ds_read_b128 v[120:123], v35
	ds_read_b128 v[124:127], v35 offset:4352
	ds_read_b128 v[128:131], v35 offset:8704
	ds_read_b128 v[132:135], v35 offset:13056
	ds_read_b128 v[136:139], v35 offset:17408
	ds_read_b128 v[140:143], v35 offset:21760
	ds_read_b128 v[144:147], v35 offset:26112
	ds_read_b128 v[148:151], v35 offset:30464
	s_cmp_lt_u32 s9, 2
	s_cbranch_scc1 .Lsgu_a_k0
	ds_read_b128 v[152:155], v35 offset:64
	ds_read_b128 v[156:159], v35 offset:4416
	ds_read_b128 v[160:163], v35 offset:8768
	ds_read_b128 v[84:87], v35 offset:13120
	ds_read_b128 v[88:91], v35 offset:17472
	ds_read_b128 v[92:95], v35 offset:21824
	ds_read_b128 v[172:175], v35 offset:26176
	ds_read_b128 v[176:179], v35 offset:30528
	s_waitcnt vmcnt(3)
	s_waitcnt lgkmcnt(8)
	v_mfma_f32_16x16x32_bf16 v[24:27], v[104:107], v[120:123], v[24:27]
	v_mfma_f32_16x16x32_bf16 v[28:31], v[104:107], v[124:127], v[28:31]
	v_mfma_f32_16x16x32_bf16 v[20:23], v[104:107], v[128:131], v[20:23]
	v_mfma_f32_16x16x32_bf16 v[16:19], v[104:107], v[132:135], v[16:19]
	v_mfma_f32_16x16x32_bf16 v[12:15], v[104:107], v[136:139], v[12:15]
	v_mfma_f32_16x16x32_bf16 v[8:11], v[104:107], v[140:143], v[8:11]
	v_mfma_f32_16x16x32_bf16 v[4:7], v[104:107], v[144:147], v[4:7]
	v_mfma_f32_16x16x32_bf16 v[0:3], v[104:107], v[148:151], v[0:3]
	s_cmp_lt_u32 s9, 3
	s_cbranch_scc1 .Lsgu_a_k1
	ds_read_b128 v[120:123], v35 offset:128
	ds_read_b128 v[124:127], v35 offset:4480
	ds_read_b128 v[128:131], v35 offset:8832
	ds_read_b128 v[132:135], v35 offset:13184
	ds_read_b128 v[136:139], v35 offset:17536
	ds_read_b128 v[140:143], v35 offset:21888
	ds_read_b128 v[144:147], v35 offset:26240
	ds_read_b128 v[148:151], v35 offset:30592
	s_waitcnt vmcnt(2)
	s_waitcnt lgkmcnt(8)
	v_mfma_f32_16x16x32_bf16 v[24:27], v[108:111], v[152:155], v[24:27]
	v_mfma_f32_16x16x32_bf16 v[28:31], v[108:111], v[156:159], v[28:31]
	v_mfma_f32_16x16x32_bf16 v[20:23], v[108:111], v[160:163], v[20:23]
	v_mfma_f32_16x16x32_bf16 v[16:19], v[108:111], v[84:87], v[16:19]
	v_mfma_f32_16x16x32_bf16 v[12:15], v[108:111], v[88:91], v[12:15]
	v_mfma_f32_16x16x32_bf16 v[8:11], v[108:111], v[92:95], v[8:11]
	v_mfma_f32_16x16x32_bf16 v[4:7], v[108:111], v[172:175], v[4:7]
	v_mfma_f32_16x16x32_bf16 v[0:3], v[108:111], v[176:179], v[0:3]
	s_cmp_lt_u32 s9, 4
	s_cbranch_scc1 .Lsgu_a_k2
	ds_read_b128 v[152:155], v35 offset:192
	ds_read_b128 v[156:159], v35 offset:4544
	ds_read_b128 v[160:163], v35 offset:8896
	ds_read_b128 v[84:87], v35 offset:13248
	ds_read_b128 v[88:91], v35 offset:17600
	ds_read_b128 v[92:95], v35 offset:21952
	ds_read_b128 v[172:175], v35 offset:26304
	ds_read_b128 v[176:179], v35 offset:30656
	s_waitcnt vmcnt(1)
	s_waitcnt lgkmcnt(8)
	v_mfma_f32_16x16x32_bf16 v[24:27], v[112:115], v[120:123], v[24:27]
	v_mfma_f32_16x16x32_bf16 v[28:31], v[112:115], v[124:127], v[28:31]
	v_mfma_f32_16x16x32_bf16 v[20:23], v[112:115], v[128:131], v[20:23]
	v_mfma_f32_16x16x32_bf16 v[16:19], v[112:115], v[132:135], v[16:19]
	v_mfma_f32_16x16x32_bf16 v[12:15], v[112:115], v[136:139], v[12:15]
	v_mfma_f32_16x16x32_bf16 v[8:11], v[112:115], v[140:143], v[8:11]
	v_mfma_f32_16x16x32_bf16 v[4:7], v[112:115], v[144:147], v[4:7]
	v_mfma_f32_16x16x32_bf16 v[0:3], v[112:115], v[148:151], v[0:3]
	s_waitcnt vmcnt(0)
	s_waitcnt lgkmcnt(0)
	v_mfma_f32_16x16x32_bf16 v[24:27], v[116:119], v[152:155], v[24:27]
	v_mfma_f32_16x16x32_bf16 v[28:31], v[116:119], v[156:159], v[28:31]
	v_mfma_f32_16x16x32_bf16 v[20:23], v[116:119], v[160:163], v[20:23]
	v_mfma_f32_16x16x32_bf16 v[16:19], v[116:119], v[84:87], v[16:19]
	v_mfma_f32_16x16x32_bf16 v[12:15], v[116:119], v[88:91], v[12:15]
	v_mfma_f32_16x16x32_bf16 v[8:11], v[116:119], v[92:95], v[8:11]
	v_mfma_f32_16x16x32_bf16 v[4:7], v[116:119], v[172:175], v[4:7]
	v_mfma_f32_16x16x32_bf16 v[0:3], v[116:119], v[176:179], v[0:3]
	s_branch .Lsgu_a_done
.Lsgu_a_k0:
	s_waitcnt vmcnt(3)
	s_waitcnt lgkmcnt(0)
	v_mfma_f32_16x16x32_bf16 v[24:27], v[104:107], v[120:123], v[24:27]
	v_mfma_f32_16x16x32_bf16 v[28:31], v[104:107], v[124:127], v[28:31]
	v_mfma_f32_16x16x32_bf16 v[20:23], v[104:107], v[128:131], v[20:23]
	v_mfma_f32_16x16x32_bf16 v[16:19], v[104:107], v[132:135], v[16:19]
	v_mfma_f32_16x16x32_bf16 v[12:15], v[104:107], v[136:139], v[12:15]
	v_mfma_f32_16x16x32_bf16 v[8:11], v[104:107], v[140:143], v[8:11]
	v_mfma_f32_16x16x32_bf16 v[4:7], v[104:107], v[144:147], v[4:7]
	v_mfma_f32_16x16x32_bf16 v[0:3], v[104:107], v[148:151], v[0:3]
	s_branch .Lsgu_a_done
.Lsgu_a_k1:
	s_waitcnt vmcnt(2)
	s_waitcnt lgkmcnt(0)
	v_mfma_f32_16x16x32_bf16 v[24:27], v[108:111], v[152:155], v[24:27]
	v_mfma_f32_16x16x32_bf16 v[28:31], v[108:111], v[156:159], v[28:31]
	v_mfma_f32_16x16x32_bf16 v[20:23], v[108:111], v[160:163], v[20:23]
	v_mfma_f32_16x16x32_bf16 v[16:19], v[108:111], v[84:87], v[16:19]
	v_mfma_f32_16x16x32_bf16 v[12:15], v[108:111], v[88:91], v[12:15]
	v_mfma_f32_16x16x32_bf16 v[8:11], v[108:111], v[92:95], v[8:11]
	v_mfma_f32_16x16x32_bf16 v[4:7], v[108:111], v[172:175], v[4:7]
	v_mfma_f32_16x16x32_bf16 v[0:3], v[108:111], v[176:179], v[0:3]
	s_branch .Lsgu_a_done
.Lsgu_a_k2:
	s_waitcnt vmcnt(1)
	s_waitcnt lgkmcnt(0)
	v_mfma_f32_16x16x32_bf16 v[24:27], v[112:115], v[120:123], v[24:27]
	v_mfma_f32_16x16x32_bf16 v[28:31], v[112:115], v[124:127], v[28:31]
	v_mfma_f32_16x16x32_bf16 v[20:23], v[112:115], v[128:131], v[20:23]
	v_mfma_f32_16x16x32_bf16 v[16:19], v[112:115], v[132:135], v[16:19]
	v_mfma_f32_16x16x32_bf16 v[12:15], v[112:115], v[136:139], v[12:15]
	v_mfma_f32_16x16x32_bf16 v[8:11], v[112:115], v[140:143], v[8:11]
	v_mfma_f32_16x16x32_bf16 v[4:7], v[112:115], v[144:147], v[4:7]
	v_mfma_f32_16x16x32_bf16 v[0:3], v[112:115], v[148:151], v[0:3]
.Lsgu_a_done:
	s_mov_b32 s9, 0
	s_branch .LBB0_109

.LBB0_128:
	global_load_dwordx4 v[104:107], v[32:33], off
	global_load_dwordx4 v[108:111], v[32:33], off offset:64
	global_load_dwordx4 v[112:115], v[32:33], off offset:128
	global_load_dwordx4 v[116:119], v[32:33], off offset:192
	ds_read_b128 v[120:123], v35
	ds_read_b128 v[124:127], v35 offset:4352
	ds_read_b128 v[128:131], v35 offset:8704
	ds_read_b128 v[132:135], v35 offset:13056
	ds_read_b128 v[136:139], v35 offset:17408
	ds_read_b128 v[140:143], v35 offset:21760
	ds_read_b128 v[144:147], v35 offset:26112
	ds_read_b128 v[148:151], v35 offset:30464
	s_cmp_lt_u32 s11, 2
	s_cbranch_scc1 .Lsgu_b_k0
	ds_read_b128 v[152:155], v35 offset:64
	ds_read_b128 v[156:159], v35 offset:4416
	ds_read_b128 v[160:163], v35 offset:8768
	ds_read_b128 v[84:87], v35 offset:13120
	ds_read_b128 v[88:91], v35 offset:17472
	ds_read_b128 v[92:95], v35 offset:21824
	ds_read_b128 v[172:175], v35 offset:26176
	ds_read_b128 v[176:179], v35 offset:30528
	s_waitcnt vmcnt(3)
	s_waitcnt lgkmcnt(8)
	v_mfma_f32_16x16x32_bf16 v[24:27], v[104:107], v[120:123], v[24:27]
	v_mfma_f32_16x16x32_bf16 v[28:31], v[104:107], v[124:127], v[28:31]
	v_mfma_f32_16x16x32_bf16 v[20:23], v[104:107], v[128:131], v[20:23]
	v_mfma_f32_16x16x32_bf16 v[16:19], v[104:107], v[132:135], v[16:19]
	v_mfma_f32_16x16x32_bf16 v[12:15], v[104:107], v[136:139], v[12:15]
	v_mfma_f32_16x16x32_bf16 v[8:11], v[104:107], v[140:143], v[8:11]
	v_mfma_f32_16x16x32_bf16 v[4:7], v[104:107], v[144:147], v[4:7]
	v_mfma_f32_16x16x32_bf16 v[0:3], v[104:107], v[148:151], v[0:3]
	s_cmp_lt_u32 s11, 3
	s_cbranch_scc1 .Lsgu_b_k1
	ds_read_b128 v[120:123], v35 offset:128
	ds_read_b128 v[124:127], v35 offset:4480
	ds_read_b128 v[128:131], v35 offset:8832
	ds_read_b128 v[132:135], v35 offset:13184
	ds_read_b128 v[136:139], v35 offset:17536
	ds_read_b128 v[140:143], v35 offset:21888
	ds_read_b128 v[144:147], v35 offset:26240
	ds_read_b128 v[148:151], v35 offset:30592
	s_waitcnt vmcnt(2)
	s_waitcnt lgkmcnt(8)
	v_mfma_f32_16x16x32_bf16 v[24:27], v[108:111], v[152:155], v[24:27]
	v_mfma_f32_16x16x32_bf16 v[28:31], v[108:111], v[156:159], v[28:31]
	v_mfma_f32_16x16x32_bf16 v[20:23], v[108:111], v[160:163], v[20:23]
	v_mfma_f32_16x16x32_bf16 v[16:19], v[108:111], v[84:87], v[16:19]
	v_mfma_f32_16x16x32_bf16 v[12:15], v[108:111], v[88:91], v[12:15]
	v_mfma_f32_16x16x32_bf16 v[8:11], v[108:111], v[92:95], v[8:11]
	v_mfma_f32_16x16x32_bf16 v[4:7], v[108:111], v[172:175], v[4:7]
	v_mfma_f32_16x16x32_bf16 v[0:3], v[108:111], v[176:179], v[0:3]
	s_cmp_lt_u32 s11, 4
	s_cbranch_scc1 .Lsgu_b_k2
	ds_read_b128 v[152:155], v35 offset:192
	ds_read_b128 v[156:159], v35 offset:4544
	ds_read_b128 v[160:163], v35 offset:8896
	ds_read_b128 v[84:87], v35 offset:13248
	ds_read_b128 v[88:91], v35 offset:17600
	ds_read_b128 v[92:95], v35 offset:21952
	ds_read_b128 v[172:175], v35 offset:26304
	ds_read_b128 v[176:179], v35 offset:30656
	s_waitcnt vmcnt(1)
	s_waitcnt lgkmcnt(8)
	v_mfma_f32_16x16x32_bf16 v[24:27], v[112:115], v[120:123], v[24:27]
	v_mfma_f32_16x16x32_bf16 v[28:31], v[112:115], v[124:127], v[28:31]
	v_mfma_f32_16x16x32_bf16 v[20:23], v[112:115], v[128:131], v[20:23]
	v_mfma_f32_16x16x32_bf16 v[16:19], v[112:115], v[132:135], v[16:19]
	v_mfma_f32_16x16x32_bf16 v[12:15], v[112:115], v[136:139], v[12:15]
	v_mfma_f32_16x16x32_bf16 v[8:11], v[112:115], v[140:143], v[8:11]
	v_mfma_f32_16x16x32_bf16 v[4:7], v[112:115], v[144:147], v[4:7]
	v_mfma_f32_16x16x32_bf16 v[0:3], v[112:115], v[148:151], v[0:3]
	s_waitcnt vmcnt(0)
	s_waitcnt lgkmcnt(0)
	v_mfma_f32_16x16x32_bf16 v[24:27], v[116:119], v[152:155], v[24:27]
	v_mfma_f32_16x16x32_bf16 v[28:31], v[116:119], v[156:159], v[28:31]
	v_mfma_f32_16x16x32_bf16 v[20:23], v[116:119], v[160:163], v[20:23]
	v_mfma_f32_16x16x32_bf16 v[16:19], v[116:119], v[84:87], v[16:19]
	v_mfma_f32_16x16x32_bf16 v[12:15], v[116:119], v[88:91], v[12:15]
	v_mfma_f32_16x16x32_bf16 v[8:11], v[116:119], v[92:95], v[8:11]
	v_mfma_f32_16x16x32_bf16 v[4:7], v[116:119], v[172:175], v[4:7]
	v_mfma_f32_16x16x32_bf16 v[0:3], v[116:119], v[176:179], v[0:3]
	s_branch .Lsgu_b_done

.Lsgu_b_done:
	s_mov_b32 s11, 0
	s_branch .LBB0_121

.LBB0_573:
	s_or_saveexec_b64 s[0:1], s[0:1]
	v_mov_b32_e32 v11, 0
	v_mov_b32_e32 v10, 0
	v_mov_b32_e32 v9, 0
	v_mov_b32_e32 v8, 0
	v_mov_b32_e32 v15, 0
	v_mov_b32_e32 v14, 0
	v_mov_b32_e32 v13, 0
	v_mov_b32_e32 v12, 0
	s_xor_b64 exec, exec, s[0:1]
	s_cbranch_execz .LBB0_575
	v_ashrrev_i32_e32 v79, 31, v78
	v_lshlrev_b64 v[2:3], 11, v[78:79]
	v_lshl_add_u64 v[2:3], v[36:37], 0, v[2:3]
	global_load_dwordx4 v[12:15], v[2:3], off offset:16
	global_load_dwordx4 v[8:11], v[2:3], off
	v_mov_b32_e32 v7, 0
	v_mov_b32_e32 v6, 0
	v_mov_b32_e32 v5, 0
	v_mov_b32_e32 v4, 0

.LBB0_579:
	s_or_saveexec_b64 s[4:5], s[4:5]
	v_mov_b32_e32 v3, 0
	v_mov_b32_e32 v2, 0
	v_mov_b32_e32 v1, 0
	v_mov_b32_e32 v0, 0
	s_xor_b64 exec, exec, s[4:5]
	s_cbranch_execz .LBB0_581
	v_ashrrev_i32_e32 v81, 31, v80
	v_lshlrev_b64 v[0:1], 11, v[80:81]
	v_lshl_add_u64 v[16:17], v[36:37], 0, v[0:1]
	global_load_dwordx4 v[0:3], v[16:17], off offset:16
	global_load_dwordx4 v[20:23], v[16:17], off
	v_mov_b32_e32 v27, 0
	v_mov_b32_e32 v16, s83
	v_mov_b32_e32 v17, s83
	v_mov_b32_e32 v18, s83
	v_mov_b32_e32 v19, s83
	v_mov_b32_e32 v26, v27
	v_mov_b32_e32 v25, v27
	v_mov_b32_e32 v24, v27

.LBB0_585:
	s_or_saveexec_b64 s[6:7], s[6:7]
	v_mov_b32_e32 v35, 0
	v_mov_b32_e32 v34, 0
	v_mov_b32_e32 v33, 0
	v_mov_b32_e32 v32, 0
	s_xor_b64 exec, exec, s[6:7]
	s_cbranch_execz .LBB0_587
	v_ashrrev_i32_e32 v83, 31, v82
	v_lshlrev_b64 v[16:17], 11, v[82:83]
	v_lshl_add_u64 v[16:17], v[36:37], 0, v[16:17]
	global_load_dwordx4 v[32:35], v[16:17], off offset:16
	s_nop 0
	global_load_dwordx4 v[16:19], v[16:17], off
	v_mov_b32_e32 v31, 0
	v_mov_b32_e32 v30, v31
	v_mov_b32_e32 v29, v31
	v_mov_b32_e32 v28, v31

.LBB0_609:
	s_or_saveexec_b64 s[0:1], s[0:1]
	v_mov_b32_e32 v11, 0
	v_mov_b32_e32 v10, 0
	v_mov_b32_e32 v9, 0
	v_mov_b32_e32 v8, 0
	v_mov_b32_e32 v15, 0
	v_mov_b32_e32 v14, 0
	v_mov_b32_e32 v13, 0
	v_mov_b32_e32 v12, 0
	s_xor_b64 exec, exec, s[0:1]
	s_cbranch_execz .LBB0_611
	v_ashrrev_i32_e32 v79, 31, v78
	v_lshlrev_b64 v[2:3], 11, v[78:79]
	v_lshl_add_u64 v[2:3], v[24:25], 0, v[2:3]
	global_load_dwordx4 v[12:15], v[2:3], off offset:16
	global_load_dwordx4 v[8:11], v[2:3], off
	v_mov_b32_e32 v7, 0
	v_mov_b32_e32 v6, 0
	v_mov_b32_e32 v5, 0
	v_mov_b32_e32 v4, 0

.LBB0_615:
	s_andn2_saveexec_b64 s[4:5], s[4:5]
	s_cbranch_execz .LBB0_617
	v_ashrrev_i32_e32 v81, 31, v80
	v_lshlrev_b64 v[0:1], 11, v[80:81]
	v_lshl_add_u64 v[0:1], v[24:25], 0, v[0:1]
	global_load_dwordx4 v[20:23], v[0:1], off offset:16
	global_load_dwordx4 v[16:19], v[0:1], off
	v_mov_b32_e32 v3, 0
	v_mov_b32_e32 v2, v3
	v_mov_b32_e32 v1, v3
	v_mov_b32_e32 v0, v3

.LBB0_631:
	s_or_saveexec_b64 s[4:5], s[4:5]
	v_mov_b32_e32 v15, 0
	v_mov_b32_e32 v14, 0
	v_mov_b32_e32 v13, 0
	v_mov_b32_e32 v12, 0
	v_mov_b32_e32 v11, 0
	v_mov_b32_e32 v10, 0
	v_mov_b32_e32 v9, 0
	v_mov_b32_e32 v8, 0
	s_xor_b64 exec, exec, s[4:5]
	s_cbranch_execz .LBB0_633
	v_ashrrev_i32_e32 v79, 31, v78
	v_lshlrev_b64 v[2:3], 11, v[78:79]
	v_lshl_add_u64 v[2:3], v[84:85], 0, v[2:3]
	global_load_dwordx4 v[8:11], v[2:3], off
	global_load_dwordx4 v[12:15], v[2:3], off offset:16
	v_mov_b32_e32 v7, 0
	v_mov_b32_e32 v6, 0
	v_mov_b32_e32 v5, 0
	v_mov_b32_e32 v4, 0

.LBB0_637:
	s_or_saveexec_b64 s[4:5], s[4:5]
	v_mov_b32_e32 v23, 0
	v_mov_b32_e32 v22, 0
	v_mov_b32_e32 v21, 0
	v_mov_b32_e32 v20, 0
	v_mov_b32_e32 v3, 0
	v_mov_b32_e32 v2, 0
	v_mov_b32_e32 v1, 0
	v_mov_b32_e32 v0, 0
	s_xor_b64 exec, exec, s[4:5]
	s_cbranch_execz .LBB0_639
	v_ashrrev_i32_e32 v81, 31, v80
	v_lshlrev_b64 v[0:1], 11, v[80:81]
	v_lshl_add_u64 v[16:17], v[84:85], 0, v[0:1]
	global_load_dwordx4 v[0:3], v[16:17], off
	global_load_dwordx4 v[20:23], v[16:17], off offset:16
	v_mov_b32_e32 v19, 0
	v_mov_b32_e32 v18, v19
	v_mov_b32_e32 v17, v19
	v_mov_b32_e32 v16, v19

.LBB0_643:
	s_or_saveexec_b64 s[6:7], s[6:7]
	v_mov_b32_e32 v39, 0
	v_mov_b32_e32 v38, 0
	v_mov_b32_e32 v37, 0
	v_mov_b32_e32 v36, 0
	v_mov_b32_e32 v35, 0
	v_mov_b32_e32 v34, 0
	v_mov_b32_e32 v33, 0
	v_mov_b32_e32 v32, 0
	s_xor_b64 exec, exec, s[6:7]
	s_cbranch_execz .LBB0_645
	v_ashrrev_i32_e32 v83, 31, v82
	v_lshlrev_b64 v[26:27], 11, v[82:83]
	v_lshl_add_u64 v[26:27], v[84:85], 0, v[26:27]
	global_load_dwordx4 v[32:35], v[26:27], off
	global_load_dwordx4 v[36:39], v[26:27], off offset:16
	v_mov_b32_e32 v31, 0
	v_mov_b32_e32 v30, v31
	v_mov_b32_e32 v29, v31
	v_mov_b32_e32 v28, v31

.LBB0_649:
	s_or_saveexec_b64 s[8:9], s[8:9]
	v_mov_b32_e32 v47, 0
	v_mov_b32_e32 v46, 0
	v_mov_b32_e32 v45, 0
	v_mov_b32_e32 v44, 0
	v_mov_b32_e32 v27, 0
	v_mov_b32_e32 v26, 0
	v_mov_b32_e32 v25, 0
	v_mov_b32_e32 v24, 0
	s_xor_b64 exec, exec, s[8:9]
	s_cbranch_execz .LBB0_651
	v_ashrrev_i32_e32 v89, 31, v88
	v_lshlrev_b64 v[24:25], 11, v[88:89]
	v_lshl_add_u64 v[40:41], v[84:85], 0, v[24:25]
	global_load_dwordx4 v[24:27], v[40:41], off
	global_load_dwordx4 v[44:47], v[40:41], off offset:16
	v_mov_b32_e32 v43, 0
	v_mov_b32_e32 v42, v43
	v_mov_b32_e32 v41, v43
	v_mov_b32_e32 v40, v43

.LBB0_655:
	s_or_saveexec_b64 s[12:13], s[12:13]
	v_mov_b32_e32 v59, 0
	v_mov_b32_e32 v58, 0
	v_mov_b32_e32 v57, 0
	v_mov_b32_e32 v56, 0
	v_mov_b32_e32 v55, 0
	v_mov_b32_e32 v54, 0
	v_mov_b32_e32 v53, 0
	v_mov_b32_e32 v52, 0
	s_xor_b64 exec, exec, s[12:13]
	s_cbranch_execz .LBB0_657
	v_ashrrev_i32_e32 v91, 31, v90
	v_lshlrev_b64 v[48:49], 11, v[90:91]
	v_lshl_add_u64 v[48:49], v[84:85], 0, v[48:49]
	global_load_dwordx4 v[52:55], v[48:49], off
	global_load_dwordx4 v[56:59], v[48:49], off offset:16
	v_mov_b32_e32 v51, 0
	v_mov_b32_e32 v50, v51
	v_mov_b32_e32 v49, v51
	v_mov_b32_e32 v48, v51

.LBB0_1051:
	s_cmp_eq_u32 s50, 0
	s_cselect_b64 s[20:21], -1, 0
	s_or_b64 s[20:21], s[34:35], s[20:21]
	s_and_b32 s54, s93, 6
	s_cmp_lg_u32 s54, 0
	s_cselect_b64 vcc, -1, 0
	s_or_b64 s[20:21], s[20:21], vcc
	s_and_b64 vcc, exec, s[20:21]
	s_cbranch_vccnz .LBB0_1050
	v_mov_b32_e32 v202, v194
	v_mov_b32_e32 v128, v198
	s_nop 0
	v_ashrrev_i32_e32 v129, 31, v128
	v_lshlrev_b64 v[212:213], 1, v[128:129]
	s_add_u32 s20, s79, s50
	s_addc_u32 s21, s92, s51
	v_add_u32_e32 v205, s63, v202
	v_mad_i64_i32 v[242:243], vcc, v205, s76, v[212:213]
	v_lshl_add_u64 v[242:243], s[20:21], 0, v[242:243]
	v_add_co_u32_e32 v242, vcc, s78, v242
	s_nop 1
	v_addc_co_u32_e32 v243, vcc, 0, v243, vcc
	global_load_dwordx4 v[128:131], v[242:243], off
	global_load_dwordx4 v[132:135], v[242:243], off offset:2048
	global_load_dwordx4 v[136:139], v[242:243], off offset:256
	global_load_dwordx4 v[140:143], v[242:243], off offset:2304
	v_add_u32_e32 v205, s63, v202
	v_add_u32_e32 v205, 16, v205
	v_mad_i64_i32 v[242:243], vcc, v205, s76, v[212:213]
	v_lshl_add_u64 v[242:243], s[20:21], 0, v[242:243]
	v_add_co_u32_e32 v242, vcc, s78, v242
	s_nop 1
	v_addc_co_u32_e32 v243, vcc, 0, v243, vcc
	global_load_dwordx4 v[144:147], v[242:243], off
	global_load_dwordx4 v[148:151], v[242:243], off offset:2048
	global_load_dwordx4 v[152:155], v[242:243], off offset:256
	global_load_dwordx4 v[156:159], v[242:243], off offset:2304
	v_add_u32_e32 v205, s63, v202
	v_add_u32_e32 v205, 32, v205
	v_mad_i64_i32 v[242:243], vcc, v205, s76, v[212:213]
	v_lshl_add_u64 v[242:243], s[20:21], 0, v[242:243]
	v_add_co_u32_e32 v242, vcc, s78, v242
	s_nop 1
	v_addc_co_u32_e32 v243, vcc, 0, v243, vcc
	global_load_dwordx4 v[160:163], v[242:243], off
	global_load_dwordx4 v[164:167], v[242:243], off offset:2048
	global_load_dwordx4 v[168:171], v[242:243], off offset:256
	global_load_dwordx4 v[172:175], v[242:243], off offset:2304
	v_add_u32_e32 v205, s63, v202
	v_add_u32_e32 v205, 48, v205
	v_mad_i64_i32 v[242:243], vcc, v205, s76, v[212:213]
	v_lshl_add_u64 v[242:243], s[20:21], 0, v[242:243]
	v_add_co_u32_e32 v242, vcc, s78, v242
	s_nop 1
	v_addc_co_u32_e32 v243, vcc, 0, v243, vcc
	global_load_dwordx4 v[176:179], v[242:243], off
	global_load_dwordx4 v[180:183], v[242:243], off offset:2048
	global_load_dwordx4 v[184:187], v[242:243], off offset:256
	global_load_dwordx4 v[188:191], v[242:243], off offset:2304
	s_waitcnt vmcnt(14)
	v_lshlrev_b32_e32 v244, 16, v128
	v_and_b32_e32 v245, 0xffff0000, v128
	v_lshlrev_b32_e32 v246, 16, v132
	v_and_b32_e32 v247, 0xffff0000, v132
	v_max_f32_e32 v244, 0x1e3ce508, v244
	v_max_f32_e32 v245, 0x1e3ce508, v245
	v_max_f32_e32 v246, 0x1e3ce508, v246
	v_max_f32_e32 v247, 0x1e3ce508, v247
	v_rcp_f32_e32 v246, v246
	v_rcp_f32_e32 v247, v247
	v_lshlrev_b32_e32 v230, 16, v129
	v_and_b32_e32 v231, 0xffff0000, v129
	v_lshlrev_b32_e32 v232, 16, v133
	v_and_b32_e32 v233, 0xffff0000, v133
	v_max_f32_e32 v230, 0x1e3ce508, v230
	v_max_f32_e32 v231, 0x1e3ce508, v231
	v_max_f32_e32 v232, 0x1e3ce508, v232
	v_max_f32_e32 v233, 0x1e3ce508, v233
	v_rcp_f32_e32 v232, v232
	v_rcp_f32_e32 v233, v233
	v_pk_mul_f32 v[244:245], v[244:245], v[246:247]
	v_pk_mul_f32 v[124:125], v[124:125], v[244:245]
	v_lshlrev_b32_e32 v244, 16, v130
	v_and_b32_e32 v245, 0xffff0000, v130
	v_lshlrev_b32_e32 v246, 16, v134
	v_and_b32_e32 v247, 0xffff0000, v134
	v_max_f32_e32 v244, 0x1e3ce508, v244
	v_max_f32_e32 v245, 0x1e3ce508, v245
	v_max_f32_e32 v246, 0x1e3ce508, v246
	v_max_f32_e32 v247, 0x1e3ce508, v247
	v_rcp_f32_e32 v246, v246
	v_rcp_f32_e32 v247, v247
	v_pk_mul_f32 v[230:231], v[230:231], v[232:233]
	v_pk_mul_f32 v[126:127], v[126:127], v[230:231]
	v_lshlrev_b32_e32 v230, 16, v131
	v_and_b32_e32 v231, 0xffff0000, v131
	v_lshlrev_b32_e32 v232, 16, v135
	v_and_b32_e32 v233, 0xffff0000, v135
	v_max_f32_e32 v230, 0x1e3ce508, v230
	v_max_f32_e32 v231, 0x1e3ce508, v231
	v_max_f32_e32 v232, 0x1e3ce508, v232
	v_max_f32_e32 v233, 0x1e3ce508, v233
	v_rcp_f32_e32 v232, v232
	v_rcp_f32_e32 v233, v233
	v_pk_mul_f32 v[244:245], v[244:245], v[246:247]
	v_pk_mul_f32 v[120:121], v[120:121], v[244:245]
	s_waitcnt vmcnt(12)
	v_lshlrev_b32_e32 v244, 16, v136
	v_and_b32_e32 v245, 0xffff0000, v136
	v_lshlrev_b32_e32 v246, 16, v140
	v_and_b32_e32 v247, 0xffff0000, v140
	v_max_f32_e32 v244, 0x1e3ce508, v244
	v_max_f32_e32 v245, 0x1e3ce508, v245
	v_max_f32_e32 v246, 0x1e3ce508, v246
	v_max_f32_e32 v247, 0x1e3ce508, v247
	v_rcp_f32_e32 v246, v246
	v_rcp_f32_e32 v247, v247
	v_pk_mul_f32 v[230:231], v[230:231], v[232:233]
	v_pk_mul_f32 v[122:123], v[122:123], v[230:231]
	v_lshlrev_b32_e32 v230, 16, v137
	v_and_b32_e32 v231, 0xffff0000, v137
	v_lshlrev_b32_e32 v232, 16, v141
	v_and_b32_e32 v233, 0xffff0000, v141
	v_max_f32_e32 v230, 0x1e3ce508, v230
	v_max_f32_e32 v231, 0x1e3ce508, v231
	v_max_f32_e32 v232, 0x1e3ce508, v232
	v_max_f32_e32 v233, 0x1e3ce508, v233
	v_rcp_f32_e32 v232, v232
	v_rcp_f32_e32 v233, v233
	v_pk_mul_f32 v[244:245], v[244:245], v[246:247]
	v_pk_mul_f32 v[92:93], v[92:93], v[244:245]
	v_lshlrev_b32_e32 v244, 16, v138
	v_and_b32_e32 v245, 0xffff0000, v138
	v_lshlrev_b32_e32 v246, 16, v142
	v_and_b32_e32 v247, 0xffff0000, v142
	v_max_f32_e32 v244, 0x1e3ce508, v244
	v_max_f32_e32 v245, 0x1e3ce508, v245
	v_max_f32_e32 v246, 0x1e3ce508, v246
	v_max_f32_e32 v247, 0x1e3ce508, v247
	v_rcp_f32_e32 v246, v246
	v_rcp_f32_e32 v247, v247
	v_pk_mul_f32 v[230:231], v[230:231], v[232:233]
	v_pk_mul_f32 v[94:95], v[94:95], v[230:231]
	v_lshlrev_b32_e32 v230, 16, v139
	v_and_b32_e32 v231, 0xffff0000, v139
	v_lshlrev_b32_e32 v232, 16, v143
	v_and_b32_e32 v233, 0xffff0000, v143
	v_max_f32_e32 v230, 0x1e3ce508, v230
	v_max_f32_e32 v231, 0x1e3ce508, v231
	v_max_f32_e32 v232, 0x1e3ce508, v232
	v_max_f32_e32 v233, 0x1e3ce508, v233
	v_rcp_f32_e32 v232, v232
	v_rcp_f32_e32 v233, v233
	v_pk_mul_f32 v[244:245], v[244:245], v[246:247]
	v_pk_mul_f32 v[88:89], v[88:89], v[244:245]
	v_pk_mul_f32 v[230:231], v[230:231], v[232:233]
	v_pk_mul_f32 v[90:91], v[90:91], v[230:231]
	v_add_u32_e32 v205, s77, v202
	v_mad_i64_i32 v[242:243], vcc, v205, s76, v[212:213]
	v_lshl_add_u64 v[242:243], s[20:21], 0, v[242:243]
	v_add_co_u32_e32 v242, vcc, s78, v242
	s_nop 1
	v_addc_co_u32_e32 v243, vcc, 0, v243, vcc
	global_load_dwordx4 v[128:131], v[242:243], off
	global_load_dwordx4 v[132:135], v[242:243], off offset:2048
	global_load_dwordx4 v[136:139], v[242:243], off offset:256
	global_load_dwordx4 v[140:143], v[242:243], off offset:2304
	s_waitcnt vmcnt(14)
	v_lshlrev_b32_e32 v244, 16, v144
	v_and_b32_e32 v245, 0xffff0000, v144
	v_lshlrev_b32_e32 v246, 16, v148
	v_and_b32_e32 v247, 0xffff0000, v148
	v_max_f32_e32 v244, 0x1e3ce508, v244
	v_max_f32_e32 v245, 0x1e3ce508, v245
	v_max_f32_e32 v246, 0x1e3ce508, v246
	v_max_f32_e32 v247, 0x1e3ce508, v247
	v_rcp_f32_e32 v246, v246
	v_rcp_f32_e32 v247, v247
	v_lshlrev_b32_e32 v230, 16, v145
	v_and_b32_e32 v231, 0xffff0000, v145
	v_lshlrev_b32_e32 v232, 16, v149
	v_and_b32_e32 v233, 0xffff0000, v149
	v_max_f32_e32 v230, 0x1e3ce508, v230
	v_max_f32_e32 v231, 0x1e3ce508, v231
	v_max_f32_e32 v232, 0x1e3ce508, v232
	v_max_f32_e32 v233, 0x1e3ce508, v233
	v_rcp_f32_e32 v232, v232
	v_rcp_f32_e32 v233, v233
	v_pk_mul_f32 v[244:245], v[244:245], v[246:247]
	v_pk_mul_f32 v[116:117], v[116:117], v[244:245]
	v_lshlrev_b32_e32 v244, 16, v146
	v_and_b32_e32 v245, 0xffff0000, v146
	v_lshlrev_b32_e32 v246, 16, v150
	v_and_b32_e32 v247, 0xffff0000, v150
	v_max_f32_e32 v244, 0x1e3ce508, v244
	v_max_f32_e32 v245, 0x1e3ce508, v245
	v_max_f32_e32 v246, 0x1e3ce508, v246
	v_max_f32_e32 v247, 0x1e3ce508, v247
	v_rcp_f32_e32 v246, v246
	v_rcp_f32_e32 v247, v247
	v_pk_mul_f32 v[230:231], v[230:231], v[232:233]
	v_pk_mul_f32 v[118:119], v[118:119], v[230:231]
	v_lshlrev_b32_e32 v230, 16, v147
	v_and_b32_e32 v231, 0xffff0000, v147
	v_lshlrev_b32_e32 v232, 16, v151
	v_and_b32_e32 v233, 0xffff0000, v151
	v_max_f32_e32 v230, 0x1e3ce508, v230
	v_max_f32_e32 v231, 0x1e3ce508, v231
	v_max_f32_e32 v232, 0x1e3ce508, v232
	v_max_f32_e32 v233, 0x1e3ce508, v233
	v_rcp_f32_e32 v232, v232
	v_rcp_f32_e32 v233, v233
	v_pk_mul_f32 v[244:245], v[244:245], v[246:247]
	v_pk_mul_f32 v[112:113], v[112:113], v[244:245]
	s_waitcnt vmcnt(12)
	v_lshlrev_b32_e32 v244, 16, v152
	v_and_b32_e32 v245, 0xffff0000, v152
	v_lshlrev_b32_e32 v246, 16, v156
	v_and_b32_e32 v247, 0xffff0000, v156
	v_max_f32_e32 v244, 0x1e3ce508, v244
	v_max_f32_e32 v245, 0x1e3ce508, v245
	v_max_f32_e32 v246, 0x1e3ce508, v246
	v_max_f32_e32 v247, 0x1e3ce508, v247
	v_rcp_f32_e32 v246, v246
	v_rcp_f32_e32 v247, v247
	v_pk_mul_f32 v[230:231], v[230:231], v[232:233]
	v_pk_mul_f32 v[114:115], v[114:115], v[230:231]
	v_lshlrev_b32_e32 v230, 16, v153
	v_and_b32_e32 v231, 0xffff0000, v153
	v_lshlrev_b32_e32 v232, 16, v157
	v_and_b32_e32 v233, 0xffff0000, v157
	v_max_f32_e32 v230, 0x1e3ce508, v230
	v_max_f32_e32 v231, 0x1e3ce508, v231
	v_max_f32_e32 v232, 0x1e3ce508, v232
	v_max_f32_e32 v233, 0x1e3ce508, v233
	v_rcp_f32_e32 v232, v232
	v_rcp_f32_e32 v233, v233
	v_pk_mul_f32 v[244:245], v[244:245], v[246:247]
	v_pk_mul_f32 v[84:85], v[84:85], v[244:245]
	v_lshlrev_b32_e32 v244, 16, v154
	v_and_b32_e32 v245, 0xffff0000, v154
	v_lshlrev_b32_e32 v246, 16, v158
	v_and_b32_e32 v247, 0xffff0000, v158
	v_max_f32_e32 v244, 0x1e3ce508, v244
	v_max_f32_e32 v245, 0x1e3ce508, v245
	v_max_f32_e32 v246, 0x1e3ce508, v246
	v_max_f32_e32 v247, 0x1e3ce508, v247
	v_rcp_f32_e32 v246, v246
	v_rcp_f32_e32 v247, v247
	v_pk_mul_f32 v[230:231], v[230:231], v[232:233]
	v_pk_mul_f32 v[86:87], v[86:87], v[230:231]
	v_lshlrev_b32_e32 v230, 16, v155
	v_and_b32_e32 v231, 0xffff0000, v155
	v_lshlrev_b32_e32 v232, 16, v159
	v_and_b32_e32 v233, 0xffff0000, v159
	v_max_f32_e32 v230, 0x1e3ce508, v230
	v_max_f32_e32 v231, 0x1e3ce508, v231
	v_max_f32_e32 v232, 0x1e3ce508, v232
	v_max_f32_e32 v233, 0x1e3ce508, v233
	v_rcp_f32_e32 v232, v232
	v_rcp_f32_e32 v233, v233
	v_pk_mul_f32 v[244:245], v[244:245], v[246:247]
	v_pk_mul_f32 v[80:81], v[80:81], v[244:245]
	v_pk_mul_f32 v[230:231], v[230:231], v[232:233]
	v_pk_mul_f32 v[82:83], v[82:83], v[230:231]
	v_add_u32_e32 v205, s77, v202
	v_add_u32_e32 v205, 16, v205
	v_mad_i64_i32 v[242:243], vcc, v205, s76, v[212:213]
	v_lshl_add_u64 v[242:243], s[20:21], 0, v[242:243]
	v_add_co_u32_e32 v242, vcc, s78, v242
	s_nop 1
	v_addc_co_u32_e32 v243, vcc, 0, v243, vcc
	global_load_dwordx4 v[144:147], v[242:243], off
	global_load_dwordx4 v[148:151], v[242:243], off offset:2048
	global_load_dwordx4 v[152:155], v[242:243], off offset:256
	global_load_dwordx4 v[156:159], v[242:243], off offset:2304
	s_waitcnt vmcnt(14)
	v_lshlrev_b32_e32 v244, 16, v160
	v_and_b32_e32 v245, 0xffff0000, v160
	v_lshlrev_b32_e32 v246, 16, v164
	v_and_b32_e32 v247, 0xffff0000, v164
	v_max_f32_e32 v244, 0x1e3ce508, v244
	v_max_f32_e32 v245, 0x1e3ce508, v245
	v_max_f32_e32 v246, 0x1e3ce508, v246
	v_max_f32_e32 v247, 0x1e3ce508, v247
	v_rcp_f32_e32 v246, v246
	v_rcp_f32_e32 v247, v247
	v_lshlrev_b32_e32 v230, 16, v161
	v_and_b32_e32 v231, 0xffff0000, v161
	v_lshlrev_b32_e32 v232, 16, v165
	v_and_b32_e32 v233, 0xffff0000, v165
	v_max_f32_e32 v230, 0x1e3ce508, v230
	v_max_f32_e32 v231, 0x1e3ce508, v231
	v_max_f32_e32 v232, 0x1e3ce508, v232
	v_max_f32_e32 v233, 0x1e3ce508, v233
	v_rcp_f32_e32 v232, v232
	v_rcp_f32_e32 v233, v233
	v_pk_mul_f32 v[244:245], v[244:245], v[246:247]
	v_pk_mul_f32 v[108:109], v[108:109], v[244:245]
	v_lshlrev_b32_e32 v244, 16, v162
	v_and_b32_e32 v245, 0xffff0000, v162
	v_lshlrev_b32_e32 v246, 16, v166
	v_and_b32_e32 v247, 0xffff0000, v166
	v_max_f32_e32 v244, 0x1e3ce508, v244
	v_max_f32_e32 v245, 0x1e3ce508, v245
	v_max_f32_e32 v246, 0x1e3ce508, v246
	v_max_f32_e32 v247, 0x1e3ce508, v247
	v_rcp_f32_e32 v246, v246
	v_rcp_f32_e32 v247, v247
	v_pk_mul_f32 v[230:231], v[230:231], v[232:233]
	v_pk_mul_f32 v[110:111], v[110:111], v[230:231]
	v_lshlrev_b32_e32 v230, 16, v163
	v_and_b32_e32 v231, 0xffff0000, v163
	v_lshlrev_b32_e32 v232, 16, v167
	v_and_b32_e32 v233, 0xffff0000, v167
	v_max_f32_e32 v230, 0x1e3ce508, v230
	v_max_f32_e32 v231, 0x1e3ce508, v231
	v_max_f32_e32 v232, 0x1e3ce508, v232
	v_max_f32_e32 v233, 0x1e3ce508, v233
	v_rcp_f32_e32 v232, v232
	v_rcp_f32_e32 v233, v233
	v_pk_mul_f32 v[244:245], v[244:245], v[246:247]
	v_pk_mul_f32 v[104:105], v[104:105], v[244:245]
	s_waitcnt vmcnt(12)
	v_lshlrev_b32_e32 v244, 16, v168
	v_and_b32_e32 v245, 0xffff0000, v168
	v_lshlrev_b32_e32 v246, 16, v172
	v_and_b32_e32 v247, 0xffff0000, v172
	v_max_f32_e32 v244, 0x1e3ce508, v244
	v_max_f32_e32 v245, 0x1e3ce508, v245
	v_max_f32_e32 v246, 0x1e3ce508, v246
	v_max_f32_e32 v247, 0x1e3ce508, v247
	v_rcp_f32_e32 v246, v246
	v_rcp_f32_e32 v247, v247
	v_pk_mul_f32 v[230:231], v[230:231], v[232:233]
	v_pk_mul_f32 v[106:107], v[106:107], v[230:231]
	v_lshlrev_b32_e32 v230, 16, v169
	v_and_b32_e32 v231, 0xffff0000, v169
	v_lshlrev_b32_e32 v232, 16, v173
	v_and_b32_e32 v233, 0xffff0000, v173
	v_max_f32_e32 v230, 0x1e3ce508, v230
	v_max_f32_e32 v231, 0x1e3ce508, v231
	v_max_f32_e32 v232, 0x1e3ce508, v232
	v_max_f32_e32 v233, 0x1e3ce508, v233
	v_rcp_f32_e32 v232, v232
	v_rcp_f32_e32 v233, v233
	v_pk_mul_f32 v[244:245], v[244:245], v[246:247]
	v_pk_mul_f32 v[76:77], v[76:77], v[244:245]
	v_lshlrev_b32_e32 v244, 16, v170
	v_and_b32_e32 v245, 0xffff0000, v170
	v_lshlrev_b32_e32 v246, 16, v174
	v_and_b32_e32 v247, 0xffff0000, v174
	v_max_f32_e32 v244, 0x1e3ce508, v244
	v_max_f32_e32 v245, 0x1e3ce508, v245
	v_max_f32_e32 v246, 0x1e3ce508, v246
	v_max_f32_e32 v247, 0x1e3ce508, v247
	v_rcp_f32_e32 v246, v246
	v_rcp_f32_e32 v247, v247
	v_pk_mul_f32 v[230:231], v[230:231], v[232:233]
	v_pk_mul_f32 v[78:79], v[78:79], v[230:231]
	v_lshlrev_b32_e32 v230, 16, v171
	v_and_b32_e32 v231, 0xffff0000, v171
	v_lshlrev_b32_e32 v232, 16, v175
	v_and_b32_e32 v233, 0xffff0000, v175
	v_max_f32_e32 v230, 0x1e3ce508, v230
	v_max_f32_e32 v231, 0x1e3ce508, v231
	v_max_f32_e32 v232, 0x1e3ce508, v232
	v_max_f32_e32 v233, 0x1e3ce508, v233
	v_rcp_f32_e32 v232, v232
	v_rcp_f32_e32 v233, v233
	v_pk_mul_f32 v[244:245], v[244:245], v[246:247]
	v_pk_mul_f32 v[72:73], v[72:73], v[244:245]
	v_pk_mul_f32 v[230:231], v[230:231], v[232:233]
	v_pk_mul_f32 v[74:75], v[74:75], v[230:231]
	v_add_u32_e32 v205, s77, v202
	v_add_u32_e32 v205, 32, v205
	v_mad_i64_i32 v[242:243], vcc, v205, s76, v[212:213]
	v_lshl_add_u64 v[242:243], s[20:21], 0, v[242:243]
	v_add_co_u32_e32 v242, vcc, s78, v242
	s_nop 1
	v_addc_co_u32_e32 v243, vcc, 0, v243, vcc
	global_load_dwordx4 v[160:163], v[242:243], off
	global_load_dwordx4 v[164:167], v[242:243], off offset:2048
	global_load_dwordx4 v[168:171], v[242:243], off offset:256
	global_load_dwordx4 v[172:175], v[242:243], off offset:2304
	s_waitcnt vmcnt(14)
	v_lshlrev_b32_e32 v244, 16, v176
	v_and_b32_e32 v245, 0xffff0000, v176
	v_lshlrev_b32_e32 v246, 16, v180
	v_and_b32_e32 v247, 0xffff0000, v180
	v_max_f32_e32 v244, 0x1e3ce508, v244
	v_max_f32_e32 v245, 0x1e3ce508, v245
	v_max_f32_e32 v246, 0x1e3ce508, v246
	v_max_f32_e32 v247, 0x1e3ce508, v247
	v_rcp_f32_e32 v246, v246
	v_rcp_f32_e32 v247, v247
	v_lshlrev_b32_e32 v230, 16, v177
	v_and_b32_e32 v231, 0xffff0000, v177
	v_lshlrev_b32_e32 v232, 16, v181
	v_and_b32_e32 v233, 0xffff0000, v181
	v_max_f32_e32 v230, 0x1e3ce508, v230
	v_max_f32_e32 v231, 0x1e3ce508, v231
	v_max_f32_e32 v232, 0x1e3ce508, v232
	v_max_f32_e32 v233, 0x1e3ce508, v233
	v_rcp_f32_e32 v232, v232
	v_rcp_f32_e32 v233, v233
	v_pk_mul_f32 v[244:245], v[244:245], v[246:247]
	v_pk_mul_f32 v[100:101], v[100:101], v[244:245]
	v_lshlrev_b32_e32 v244, 16, v178
	v_and_b32_e32 v245, 0xffff0000, v178
	v_lshlrev_b32_e32 v246, 16, v182
	v_and_b32_e32 v247, 0xffff0000, v182
	v_max_f32_e32 v244, 0x1e3ce508, v244
	v_max_f32_e32 v245, 0x1e3ce508, v245
	v_max_f32_e32 v246, 0x1e3ce508, v246
	v_max_f32_e32 v247, 0x1e3ce508, v247
	v_rcp_f32_e32 v246, v246
	v_rcp_f32_e32 v247, v247
	v_pk_mul_f32 v[230:231], v[230:231], v[232:233]
	v_pk_mul_f32 v[102:103], v[102:103], v[230:231]
	v_lshlrev_b32_e32 v230, 16, v179
	v_and_b32_e32 v231, 0xffff0000, v179
	v_lshlrev_b32_e32 v232, 16, v183
	v_and_b32_e32 v233, 0xffff0000, v183
	v_max_f32_e32 v230, 0x1e3ce508, v230
	v_max_f32_e32 v231, 0x1e3ce508, v231
	v_max_f32_e32 v232, 0x1e3ce508, v232
	v_max_f32_e32 v233, 0x1e3ce508, v233
	v_rcp_f32_e32 v232, v232
	v_rcp_f32_e32 v233, v233
	v_pk_mul_f32 v[244:245], v[244:245], v[246:247]
	v_pk_mul_f32 v[96:97], v[96:97], v[244:245]
	s_waitcnt vmcnt(12)
	v_lshlrev_b32_e32 v244, 16, v184
	v_and_b32_e32 v245, 0xffff0000, v184
	v_lshlrev_b32_e32 v246, 16, v188
	v_and_b32_e32 v247, 0xffff0000, v188
	v_max_f32_e32 v244, 0x1e3ce508, v244
	v_max_f32_e32 v245, 0x1e3ce508, v245
	v_max_f32_e32 v246, 0x1e3ce508, v246
	v_max_f32_e32 v247, 0x1e3ce508, v247
	v_rcp_f32_e32 v246, v246
	v_rcp_f32_e32 v247, v247
	v_pk_mul_f32 v[230:231], v[230:231], v[232:233]
	v_pk_mul_f32 v[98:99], v[98:99], v[230:231]
	v_lshlrev_b32_e32 v230, 16, v185
	v_and_b32_e32 v231, 0xffff0000, v185
	v_lshlrev_b32_e32 v232, 16, v189
	v_and_b32_e32 v233, 0xffff0000, v189
	v_max_f32_e32 v230, 0x1e3ce508, v230
	v_max_f32_e32 v231, 0x1e3ce508, v231
	v_max_f32_e32 v232, 0x1e3ce508, v232
	v_max_f32_e32 v233, 0x1e3ce508, v233
	v_rcp_f32_e32 v232, v232
	v_rcp_f32_e32 v233, v233
	v_pk_mul_f32 v[244:245], v[244:245], v[246:247]
	v_pk_mul_f32 v[68:69], v[68:69], v[244:245]
	v_lshlrev_b32_e32 v244, 16, v186
	v_and_b32_e32 v245, 0xffff0000, v186
	v_lshlrev_b32_e32 v246, 16, v190
	v_and_b32_e32 v247, 0xffff0000, v190
	v_max_f32_e32 v244, 0x1e3ce508, v244
	v_max_f32_e32 v245, 0x1e3ce508, v245
	v_max_f32_e32 v246, 0x1e3ce508, v246
	v_max_f32_e32 v247, 0x1e3ce508, v247
	v_rcp_f32_e32 v246, v246
	v_rcp_f32_e32 v247, v247
	v_pk_mul_f32 v[230:231], v[230:231], v[232:233]
	v_pk_mul_f32 v[70:71], v[70:71], v[230:231]
	v_lshlrev_b32_e32 v230, 16, v187
	v_and_b32_e32 v231, 0xffff0000, v187
	v_lshlrev_b32_e32 v232, 16, v191
	v_and_b32_e32 v233, 0xffff0000, v191
	v_max_f32_e32 v230, 0x1e3ce508, v230
	v_max_f32_e32 v231, 0x1e3ce508, v231
	v_max_f32_e32 v232, 0x1e3ce508, v232
	v_max_f32_e32 v233, 0x1e3ce508, v233
	v_rcp_f32_e32 v232, v232
	v_rcp_f32_e32 v233, v233
	v_pk_mul_f32 v[244:245], v[244:245], v[246:247]
	v_pk_mul_f32 v[64:65], v[64:65], v[244:245]
	v_pk_mul_f32 v[230:231], v[230:231], v[232:233]
	v_pk_mul_f32 v[66:67], v[66:67], v[230:231]
	v_add_u32_e32 v205, s77, v202
	v_add_u32_e32 v205, 48, v205
	v_mad_i64_i32 v[242:243], vcc, v205, s76, v[212:213]
	v_lshl_add_u64 v[242:243], s[20:21], 0, v[242:243]
	v_add_co_u32_e32 v242, vcc, s78, v242
	s_nop 1
	v_addc_co_u32_e32 v243, vcc, 0, v243, vcc
	global_load_dwordx4 v[176:179], v[242:243], off
	global_load_dwordx4 v[180:183], v[242:243], off offset:2048
	global_load_dwordx4 v[184:187], v[242:243], off offset:256
	global_load_dwordx4 v[188:191], v[242:243], off offset:2304
	s_waitcnt vmcnt(14)
	v_lshlrev_b32_e32 v244, 16, v128
	v_and_b32_e32 v245, 0xffff0000, v128
	v_lshlrev_b32_e32 v246, 16, v132
	v_and_b32_e32 v247, 0xffff0000, v132
	v_max_f32_e32 v244, 0x1e3ce508, v244
	v_max_f32_e32 v245, 0x1e3ce508, v245
	v_max_f32_e32 v246, 0x1e3ce508, v246
	v_max_f32_e32 v247, 0x1e3ce508, v247
	v_rcp_f32_e32 v246, v246
	v_rcp_f32_e32 v247, v247
	v_lshlrev_b32_e32 v230, 16, v129
	v_and_b32_e32 v231, 0xffff0000, v129
	v_lshlrev_b32_e32 v232, 16, v133
	v_and_b32_e32 v233, 0xffff0000, v133
	v_max_f32_e32 v230, 0x1e3ce508, v230
	v_max_f32_e32 v231, 0x1e3ce508, v231
	v_max_f32_e32 v232, 0x1e3ce508, v232
	v_max_f32_e32 v233, 0x1e3ce508, v233
	v_rcp_f32_e32 v232, v232
	v_rcp_f32_e32 v233, v233
	v_pk_mul_f32 v[244:245], v[244:245], v[246:247]
	v_pk_mul_f32 v[60:61], v[60:61], v[244:245]
	v_lshlrev_b32_e32 v244, 16, v130
	v_and_b32_e32 v245, 0xffff0000, v130
	v_lshlrev_b32_e32 v246, 16, v134
	v_and_b32_e32 v247, 0xffff0000, v134
	v_max_f32_e32 v244, 0x1e3ce508, v244
	v_max_f32_e32 v245, 0x1e3ce508, v245
	v_max_f32_e32 v246, 0x1e3ce508, v246
	v_max_f32_e32 v247, 0x1e3ce508, v247
	v_rcp_f32_e32 v246, v246
	v_rcp_f32_e32 v247, v247
	v_pk_mul_f32 v[230:231], v[230:231], v[232:233]
	v_pk_mul_f32 v[62:63], v[62:63], v[230:231]
	v_lshlrev_b32_e32 v230, 16, v131
	v_and_b32_e32 v231, 0xffff0000, v131
	v_lshlrev_b32_e32 v232, 16, v135
	v_and_b32_e32 v233, 0xffff0000, v135
	v_max_f32_e32 v230, 0x1e3ce508, v230
	v_max_f32_e32 v231, 0x1e3ce508, v231
	v_max_f32_e32 v232, 0x1e3ce508, v232
	v_max_f32_e32 v233, 0x1e3ce508, v233
	v_rcp_f32_e32 v232, v232
	v_rcp_f32_e32 v233, v233
	v_pk_mul_f32 v[244:245], v[244:245], v[246:247]
	v_pk_mul_f32 v[56:57], v[56:57], v[244:245]
	s_waitcnt vmcnt(12)
	v_lshlrev_b32_e32 v244, 16, v136
	v_and_b32_e32 v245, 0xffff0000, v136
	v_lshlrev_b32_e32 v246, 16, v140
	v_and_b32_e32 v247, 0xffff0000, v140
	v_max_f32_e32 v244, 0x1e3ce508, v244
	v_max_f32_e32 v245, 0x1e3ce508, v245
	v_max_f32_e32 v246, 0x1e3ce508, v246
	v_max_f32_e32 v247, 0x1e3ce508, v247
	v_rcp_f32_e32 v246, v246
	v_rcp_f32_e32 v247, v247
	v_pk_mul_f32 v[230:231], v[230:231], v[232:233]
	v_pk_mul_f32 v[58:59], v[58:59], v[230:231]
	v_lshlrev_b32_e32 v230, 16, v137
	v_and_b32_e32 v231, 0xffff0000, v137
	v_lshlrev_b32_e32 v232, 16, v141
	v_and_b32_e32 v233, 0xffff0000, v141
	v_max_f32_e32 v230, 0x1e3ce508, v230
	v_max_f32_e32 v231, 0x1e3ce508, v231
	v_max_f32_e32 v232, 0x1e3ce508, v232
	v_max_f32_e32 v233, 0x1e3ce508, v233
	v_rcp_f32_e32 v232, v232
	v_rcp_f32_e32 v233, v233
	v_pk_mul_f32 v[244:245], v[244:245], v[246:247]
	v_pk_mul_f32 v[28:29], v[28:29], v[244:245]
	v_lshlrev_b32_e32 v244, 16, v138
	v_and_b32_e32 v245, 0xffff0000, v138
	v_lshlrev_b32_e32 v246, 16, v142
	v_and_b32_e32 v247, 0xffff0000, v142
	v_max_f32_e32 v244, 0x1e3ce508, v244
	v_max_f32_e32 v245, 0x1e3ce508, v245
	v_max_f32_e32 v246, 0x1e3ce508, v246
	v_max_f32_e32 v247, 0x1e3ce508, v247
	v_rcp_f32_e32 v246, v246
	v_rcp_f32_e32 v247, v247
	v_pk_mul_f32 v[230:231], v[230:231], v[232:233]
	v_pk_mul_f32 v[30:31], v[30:31], v[230:231]
	v_lshlrev_b32_e32 v230, 16, v139
	v_and_b32_e32 v231, 0xffff0000, v139
	v_lshlrev_b32_e32 v232, 16, v143
	v_and_b32_e32 v233, 0xffff0000, v143
	v_max_f32_e32 v230, 0x1e3ce508, v230
	v_max_f32_e32 v231, 0x1e3ce508, v231
	v_max_f32_e32 v232, 0x1e3ce508, v232
	v_max_f32_e32 v233, 0x1e3ce508, v233
	v_rcp_f32_e32 v232, v232
	v_rcp_f32_e32 v233, v233
	v_pk_mul_f32 v[244:245], v[244:245], v[246:247]
	v_pk_mul_f32 v[24:25], v[24:25], v[244:245]
	v_pk_mul_f32 v[230:231], v[230:231], v[232:233]
	v_pk_mul_f32 v[26:27], v[26:27], v[230:231]
	s_waitcnt vmcnt(10)
	v_lshlrev_b32_e32 v244, 16, v144
	v_and_b32_e32 v245, 0xffff0000, v144
	v_lshlrev_b32_e32 v246, 16, v148
	v_and_b32_e32 v247, 0xffff0000, v148
	v_max_f32_e32 v244, 0x1e3ce508, v244
	v_max_f32_e32 v245, 0x1e3ce508, v245
	v_max_f32_e32 v246, 0x1e3ce508, v246
	v_max_f32_e32 v247, 0x1e3ce508, v247
	v_rcp_f32_e32 v246, v246
	v_rcp_f32_e32 v247, v247
	v_lshlrev_b32_e32 v230, 16, v145
	v_and_b32_e32 v231, 0xffff0000, v145
	v_lshlrev_b32_e32 v232, 16, v149
	v_and_b32_e32 v233, 0xffff0000, v149
	v_max_f32_e32 v230, 0x1e3ce508, v230
	v_max_f32_e32 v231, 0x1e3ce508, v231
	v_max_f32_e32 v232, 0x1e3ce508, v232
	v_max_f32_e32 v233, 0x1e3ce508, v233
	v_rcp_f32_e32 v232, v232
	v_rcp_f32_e32 v233, v233
	v_pk_mul_f32 v[244:245], v[244:245], v[246:247]
	v_pk_mul_f32 v[52:53], v[52:53], v[244:245]
	v_lshlrev_b32_e32 v244, 16, v146
	v_and_b32_e32 v245, 0xffff0000, v146
	v_lshlrev_b32_e32 v246, 16, v150
	v_and_b32_e32 v247, 0xffff0000, v150
	v_max_f32_e32 v244, 0x1e3ce508, v244
	v_max_f32_e32 v245, 0x1e3ce508, v245
	v_max_f32_e32 v246, 0x1e3ce508, v246
	v_max_f32_e32 v247, 0x1e3ce508, v247
	v_rcp_f32_e32 v246, v246
	v_rcp_f32_e32 v247, v247
	v_pk_mul_f32 v[230:231], v[230:231], v[232:233]
	v_pk_mul_f32 v[54:55], v[54:55], v[230:231]
	v_lshlrev_b32_e32 v230, 16, v147
	v_and_b32_e32 v231, 0xffff0000, v147
	v_lshlrev_b32_e32 v232, 16, v151
	v_and_b32_e32 v233, 0xffff0000, v151
	v_max_f32_e32 v230, 0x1e3ce508, v230
	v_max_f32_e32 v231, 0x1e3ce508, v231
	v_max_f32_e32 v232, 0x1e3ce508, v232
	v_max_f32_e32 v233, 0x1e3ce508, v233
	v_rcp_f32_e32 v232, v232
	v_rcp_f32_e32 v233, v233
	v_pk_mul_f32 v[244:245], v[244:245], v[246:247]
	v_pk_mul_f32 v[48:49], v[48:49], v[244:245]
	s_waitcnt vmcnt(8)
	v_lshlrev_b32_e32 v244, 16, v152
	v_and_b32_e32 v245, 0xffff0000, v152
	v_lshlrev_b32_e32 v246, 16, v156
	v_and_b32_e32 v247, 0xffff0000, v156
	v_max_f32_e32 v244, 0x1e3ce508, v244
	v_max_f32_e32 v245, 0x1e3ce508, v245
	v_max_f32_e32 v246, 0x1e3ce508, v246
	v_max_f32_e32 v247, 0x1e3ce508, v247
	v_rcp_f32_e32 v246, v246
	v_rcp_f32_e32 v247, v247
	v_pk_mul_f32 v[230:231], v[230:231], v[232:233]
	v_pk_mul_f32 v[50:51], v[50:51], v[230:231]
	v_lshlrev_b32_e32 v230, 16, v153
	v_and_b32_e32 v231, 0xffff0000, v153
	v_lshlrev_b32_e32 v232, 16, v157
	v_and_b32_e32 v233, 0xffff0000, v157
	v_max_f32_e32 v230, 0x1e3ce508, v230
	v_max_f32_e32 v231, 0x1e3ce508, v231
	v_max_f32_e32 v232, 0x1e3ce508, v232
	v_max_f32_e32 v233, 0x1e3ce508, v233
	v_rcp_f32_e32 v232, v232
	v_rcp_f32_e32 v233, v233
	v_pk_mul_f32 v[244:245], v[244:245], v[246:247]
	v_pk_mul_f32 v[20:21], v[20:21], v[244:245]
	v_lshlrev_b32_e32 v244, 16, v154
	v_and_b32_e32 v245, 0xffff0000, v154
	v_lshlrev_b32_e32 v246, 16, v158
	v_and_b32_e32 v247, 0xffff0000, v158
	v_max_f32_e32 v244, 0x1e3ce508, v244
	v_max_f32_e32 v245, 0x1e3ce508, v245
	v_max_f32_e32 v246, 0x1e3ce508, v246
	v_max_f32_e32 v247, 0x1e3ce508, v247
	v_rcp_f32_e32 v246, v246
	v_rcp_f32_e32 v247, v247
	v_pk_mul_f32 v[230:231], v[230:231], v[232:233]
	v_pk_mul_f32 v[22:23], v[22:23], v[230:231]
	v_lshlrev_b32_e32 v230, 16, v155
	v_and_b32_e32 v231, 0xffff0000, v155
	v_lshlrev_b32_e32 v232, 16, v159
	v_and_b32_e32 v233, 0xffff0000, v159
	v_max_f32_e32 v230, 0x1e3ce508, v230
	v_max_f32_e32 v231, 0x1e3ce508, v231
	v_max_f32_e32 v232, 0x1e3ce508, v232
	v_max_f32_e32 v233, 0x1e3ce508, v233
	v_rcp_f32_e32 v232, v232
	v_rcp_f32_e32 v233, v233
	v_pk_mul_f32 v[244:245], v[244:245], v[246:247]
	v_pk_mul_f32 v[16:17], v[16:17], v[244:245]
	v_pk_mul_f32 v[230:231], v[230:231], v[232:233]
	v_pk_mul_f32 v[18:19], v[18:19], v[230:231]
	s_waitcnt vmcnt(6)
	v_lshlrev_b32_e32 v244, 16, v160
	v_and_b32_e32 v245, 0xffff0000, v160
	v_lshlrev_b32_e32 v246, 16, v164
	v_and_b32_e32 v247, 0xffff0000, v164
	v_max_f32_e32 v244, 0x1e3ce508, v244
	v_max_f32_e32 v245, 0x1e3ce508, v245
	v_max_f32_e32 v246, 0x1e3ce508, v246
	v_max_f32_e32 v247, 0x1e3ce508, v247
	v_rcp_f32_e32 v246, v246
	v_rcp_f32_e32 v247, v247
	v_lshlrev_b32_e32 v230, 16, v161
	v_and_b32_e32 v231, 0xffff0000, v161
	v_lshlrev_b32_e32 v232, 16, v165
	v_and_b32_e32 v233, 0xffff0000, v165
	v_max_f32_e32 v230, 0x1e3ce508, v230
	v_max_f32_e32 v231, 0x1e3ce508, v231
	v_max_f32_e32 v232, 0x1e3ce508, v232
	v_max_f32_e32 v233, 0x1e3ce508, v233
	v_rcp_f32_e32 v232, v232
	v_rcp_f32_e32 v233, v233
	v_pk_mul_f32 v[244:245], v[244:245], v[246:247]
	v_pk_mul_f32 v[44:45], v[44:45], v[244:245]
	v_lshlrev_b32_e32 v244, 16, v162
	v_and_b32_e32 v245, 0xffff0000, v162
	v_lshlrev_b32_e32 v246, 16, v166
	v_and_b32_e32 v247, 0xffff0000, v166
	v_max_f32_e32 v244, 0x1e3ce508, v244
	v_max_f32_e32 v245, 0x1e3ce508, v245
	v_max_f32_e32 v246, 0x1e3ce508, v246
	v_max_f32_e32 v247, 0x1e3ce508, v247
	v_rcp_f32_e32 v246, v246
	v_rcp_f32_e32 v247, v247
	v_pk_mul_f32 v[230:231], v[230:231], v[232:233]
	v_pk_mul_f32 v[46:47], v[46:47], v[230:231]
	v_lshlrev_b32_e32 v230, 16, v163
	v_and_b32_e32 v231, 0xffff0000, v163
	v_lshlrev_b32_e32 v232, 16, v167
	v_and_b32_e32 v233, 0xffff0000, v167
	v_max_f32_e32 v230, 0x1e3ce508, v230
	v_max_f32_e32 v231, 0x1e3ce508, v231
	v_max_f32_e32 v232, 0x1e3ce508, v232
	v_max_f32_e32 v233, 0x1e3ce508, v233
	v_rcp_f32_e32 v232, v232
	v_rcp_f32_e32 v233, v233
	v_pk_mul_f32 v[244:245], v[244:245], v[246:247]
	v_pk_mul_f32 v[40:41], v[40:41], v[244:245]
	s_waitcnt vmcnt(4)
	v_lshlrev_b32_e32 v244, 16, v168
	v_and_b32_e32 v245, 0xffff0000, v168
	v_lshlrev_b32_e32 v246, 16, v172
	v_and_b32_e32 v247, 0xffff0000, v172
	v_max_f32_e32 v244, 0x1e3ce508, v244
	v_max_f32_e32 v245, 0x1e3ce508, v245
	v_max_f32_e32 v246, 0x1e3ce508, v246
	v_max_f32_e32 v247, 0x1e3ce508, v247
	v_rcp_f32_e32 v246, v246
	v_rcp_f32_e32 v247, v247
	v_pk_mul_f32 v[230:231], v[230:231], v[232:233]
	v_pk_mul_f32 v[42:43], v[42:43], v[230:231]
	v_lshlrev_b32_e32 v230, 16, v169
	v_and_b32_e32 v231, 0xffff0000, v169
	v_lshlrev_b32_e32 v232, 16, v173
	v_and_b32_e32 v233, 0xffff0000, v173
	v_max_f32_e32 v230, 0x1e3ce508, v230
	v_max_f32_e32 v231, 0x1e3ce508, v231
	v_max_f32_e32 v232, 0x1e3ce508, v232
	v_max_f32_e32 v233, 0x1e3ce508, v233
	v_rcp_f32_e32 v232, v232
	v_rcp_f32_e32 v233, v233
	v_pk_mul_f32 v[244:245], v[244:245], v[246:247]
	v_pk_mul_f32 v[12:13], v[12:13], v[244:245]
	v_lshlrev_b32_e32 v244, 16, v170
	v_and_b32_e32 v245, 0xffff0000, v170
	v_lshlrev_b32_e32 v246, 16, v174
	v_and_b32_e32 v247, 0xffff0000, v174
	v_max_f32_e32 v244, 0x1e3ce508, v244
	v_max_f32_e32 v245, 0x1e3ce508, v245
	v_max_f32_e32 v246, 0x1e3ce508, v246
	v_max_f32_e32 v247, 0x1e3ce508, v247
	v_rcp_f32_e32 v246, v246
	v_rcp_f32_e32 v247, v247
	v_pk_mul_f32 v[230:231], v[230:231], v[232:233]
	v_pk_mul_f32 v[14:15], v[14:15], v[230:231]
	v_lshlrev_b32_e32 v230, 16, v171
	v_and_b32_e32 v231, 0xffff0000, v171
	v_lshlrev_b32_e32 v232, 16, v175
	v_and_b32_e32 v233, 0xffff0000, v175
	v_max_f32_e32 v230, 0x1e3ce508, v230
	v_max_f32_e32 v231, 0x1e3ce508, v231
	v_max_f32_e32 v232, 0x1e3ce508, v232
	v_max_f32_e32 v233, 0x1e3ce508, v233
	v_rcp_f32_e32 v232, v232
	v_rcp_f32_e32 v233, v233
	v_pk_mul_f32 v[244:245], v[244:245], v[246:247]
	v_pk_mul_f32 v[8:9], v[8:9], v[244:245]
	v_pk_mul_f32 v[230:231], v[230:231], v[232:233]
	v_pk_mul_f32 v[10:11], v[10:11], v[230:231]
	s_waitcnt vmcnt(2)
	v_lshlrev_b32_e32 v244, 16, v176
	v_and_b32_e32 v245, 0xffff0000, v176
	v_lshlrev_b32_e32 v246, 16, v180
	v_and_b32_e32 v247, 0xffff0000, v180
	v_max_f32_e32 v244, 0x1e3ce508, v244
	v_max_f32_e32 v245, 0x1e3ce508, v245
	v_max_f32_e32 v246, 0x1e3ce508, v246
	v_max_f32_e32 v247, 0x1e3ce508, v247
	v_rcp_f32_e32 v246, v246
	v_rcp_f32_e32 v247, v247
	v_lshlrev_b32_e32 v230, 16, v177
	v_and_b32_e32 v231, 0xffff0000, v177
	v_lshlrev_b32_e32 v232, 16, v181
	v_and_b32_e32 v233, 0xffff0000, v181
	v_max_f32_e32 v230, 0x1e3ce508, v230
	v_max_f32_e32 v231, 0x1e3ce508, v231
	v_max_f32_e32 v232, 0x1e3ce508, v232
	v_max_f32_e32 v233, 0x1e3ce508, v233
	v_rcp_f32_e32 v232, v232
	v_rcp_f32_e32 v233, v233
	v_pk_mul_f32 v[244:245], v[244:245], v[246:247]
	v_pk_mul_f32 v[36:37], v[36:37], v[244:245]
	v_lshlrev_b32_e32 v244, 16, v178
	v_and_b32_e32 v245, 0xffff0000, v178
	v_lshlrev_b32_e32 v246, 16, v182
	v_and_b32_e32 v247, 0xffff0000, v182
	v_max_f32_e32 v244, 0x1e3ce508, v244
	v_max_f32_e32 v245, 0x1e3ce508, v245
	v_max_f32_e32 v246, 0x1e3ce508, v246
	v_max_f32_e32 v247, 0x1e3ce508, v247
	v_rcp_f32_e32 v246, v246
	v_rcp_f32_e32 v247, v247
	v_pk_mul_f32 v[230:231], v[230:231], v[232:233]
	v_pk_mul_f32 v[38:39], v[38:39], v[230:231]
	v_lshlrev_b32_e32 v230, 16, v179
	v_and_b32_e32 v231, 0xffff0000, v179
	v_lshlrev_b32_e32 v232, 16, v183
	v_and_b32_e32 v233, 0xffff0000, v183
	v_max_f32_e32 v230, 0x1e3ce508, v230
	v_max_f32_e32 v231, 0x1e3ce508, v231
	v_max_f32_e32 v232, 0x1e3ce508, v232
	v_max_f32_e32 v233, 0x1e3ce508, v233
	v_rcp_f32_e32 v232, v232
	v_rcp_f32_e32 v233, v233
	v_pk_mul_f32 v[244:245], v[244:245], v[246:247]
	v_pk_mul_f32 v[32:33], v[32:33], v[244:245]
	s_waitcnt vmcnt(0)
	v_lshlrev_b32_e32 v244, 16, v184
	v_and_b32_e32 v245, 0xffff0000, v184
	v_lshlrev_b32_e32 v246, 16, v188
	v_and_b32_e32 v247, 0xffff0000, v188
	v_max_f32_e32 v244, 0x1e3ce508, v244
	v_max_f32_e32 v245, 0x1e3ce508, v245
	v_max_f32_e32 v246, 0x1e3ce508, v246
	v_max_f32_e32 v247, 0x1e3ce508, v247
	v_rcp_f32_e32 v246, v246
	v_rcp_f32_e32 v247, v247
	v_pk_mul_f32 v[230:231], v[230:231], v[232:233]
	v_pk_mul_f32 v[34:35], v[34:35], v[230:231]
	v_lshlrev_b32_e32 v230, 16, v185
	v_and_b32_e32 v231, 0xffff0000, v185
	v_lshlrev_b32_e32 v232, 16, v189
	v_and_b32_e32 v233, 0xffff0000, v189
	v_max_f32_e32 v230, 0x1e3ce508, v230
	v_max_f32_e32 v231, 0x1e3ce508, v231
	v_max_f32_e32 v232, 0x1e3ce508, v232
	v_max_f32_e32 v233, 0x1e3ce508, v233
	v_rcp_f32_e32 v232, v232
	v_rcp_f32_e32 v233, v233
	v_pk_mul_f32 v[244:245], v[244:245], v[246:247]
	v_pk_mul_f32 v[4:5], v[4:5], v[244:245]
	v_lshlrev_b32_e32 v244, 16, v186
	v_and_b32_e32 v245, 0xffff0000, v186
	v_lshlrev_b32_e32 v246, 16, v190
	v_and_b32_e32 v247, 0xffff0000, v190
	v_max_f32_e32 v244, 0x1e3ce508, v244
	v_max_f32_e32 v245, 0x1e3ce508, v245
	v_max_f32_e32 v246, 0x1e3ce508, v246
	v_max_f32_e32 v247, 0x1e3ce508, v247
	v_rcp_f32_e32 v246, v246
	v_rcp_f32_e32 v247, v247
	v_pk_mul_f32 v[230:231], v[230:231], v[232:233]
	v_pk_mul_f32 v[6:7], v[6:7], v[230:231]
	v_lshlrev_b32_e32 v230, 16, v187
	v_and_b32_e32 v231, 0xffff0000, v187
	v_lshlrev_b32_e32 v232, 16, v191
	v_and_b32_e32 v233, 0xffff0000, v191
	v_max_f32_e32 v230, 0x1e3ce508, v230
	v_max_f32_e32 v231, 0x1e3ce508, v231
	v_max_f32_e32 v232, 0x1e3ce508, v232
	v_max_f32_e32 v233, 0x1e3ce508, v233
	v_rcp_f32_e32 v232, v232
	v_rcp_f32_e32 v233, v233
	v_pk_mul_f32 v[244:245], v[244:245], v[246:247]
	v_pk_mul_f32 v[0:1], v[0:1], v[244:245]
	v_pk_mul_f32 v[230:231], v[230:231], v[232:233]
	v_pk_mul_f32 v[2:3], v[2:3], v[230:231]
	s_branch .LBB0_1050
